# phase-1 pointer-select SALU block of every GEMM K loop moved into the MFMA run (one per gap), on top of P13 rewrite
# speedup vs baseline: 1.0078x; 1.0047x over previous
.LBB0_232:
	ds_read_b128 v[158:161], v152
	ds_read_b128 v[162:165], v152 offset:1024
	ds_read_b128 v[166:169], v152 offset:2048
	ds_read_b128 v[170:173], v152 offset:3072
	s_mov_b32 m0, s47
	v_lshl_add_u64 v[206:207], v[142:143], 0, s[34:35]
	ds_read_b128 v[174:177], v153
	ds_read_b128 v[178:181], v153 offset:1024
	ds_read_b128 v[182:185], v153 offset:2048
	ds_read_b128 v[186:189], v153 offset:3072
	ds_read_b128 v[190:193], v153 offset:4096
	ds_read_b128 v[194:197], v153 offset:5120
	ds_read_b128 v[198:201], v153 offset:6144
	ds_read_b128 v[202:205], v153 offset:7168
	global_load_lds_dwordx4 v[206:207], off
	v_lshl_add_u64 v[206:207], v[144:145], 0, s[34:35]
	s_mov_b32 m0, s48
	s_nop 0
	global_load_lds_dwordx4 v[206:207], off
	s_waitcnt lgkmcnt(8)
	s_barrier
	s_waitcnt lgkmcnt(0)
	s_setprio 1
	s_waitcnt lgkmcnt(0)
	v_mfma_f32_16x16x32_bf16 v[120:123], v[158:161], v[174:177], v[120:123]
	s_add_i32 s61, s34, 0xfffc0080
	v_mfma_f32_16x16x32_bf16 v[112:115], v[166:169], v[174:177], v[112:115]
	s_cmp_eq_u32 s19, 12
	v_mfma_f32_16x16x32_bf16 v[104:107], v[158:161], v[182:185], v[104:107]
	s_cselect_b64 s[36:37], -1, 0
	v_mfma_f32_16x16x32_bf16 v[96:99], v[166:169], v[182:185], v[96:99]
	s_and_b64 s[62:63], s[36:37], exec
	v_mfma_f32_16x16x32_bf16 v[88:91], v[158:161], v[190:193], v[88:91]
	s_cselect_b32 s61, 0, s61
	v_mfma_f32_16x16x32_bf16 v[80:83], v[166:169], v[190:193], v[80:83]
	s_and_b64 s[36:37], s[30:31], s[36:37]
	v_mfma_f32_16x16x32_bf16 v[72:75], v[158:161], v[198:201], v[72:75]
	s_and_b64 s[36:37], s[36:37], exec
	v_mfma_f32_16x16x32_bf16 v[60:63], v[166:169], v[198:201], v[60:63]
	s_cselect_b32 s63, s21, s27
	v_mfma_f32_16x16x32_bf16 v[120:123], v[162:165], v[178:181], v[120:123]
	s_cselect_b32 s62, s20, s26
	v_mfma_f32_16x16x32_bf16 v[112:115], v[170:173], v[178:181], v[112:115]
	s_cselect_b32 s37, s23, s29
	v_mfma_f32_16x16x32_bf16 v[104:107], v[162:165], v[186:189], v[104:107]
	s_cselect_b32 s36, s22, s28
	v_mfma_f32_16x16x32_bf16 v[96:99], v[170:173], v[186:189], v[96:99]
	v_mfma_f32_16x16x32_bf16 v[88:91], v[162:165], v[194:197], v[88:91]
	v_mfma_f32_16x16x32_bf16 v[80:83], v[170:173], v[194:197], v[80:83]
	v_mfma_f32_16x16x32_bf16 v[72:75], v[162:165], v[202:205], v[72:75]
	v_mfma_f32_16x16x32_bf16 v[60:63], v[170:173], v[202:205], v[60:63]
	s_setprio 0
	s_barrier
	s_add_u32 s36, s36, s61
	s_addc_u32 s37, s37, 0
	s_mov_b32 m0, s49
	v_lshl_add_u64 v[218:219], s[36:37], 0, v[134:135]
	ds_read_b128 v[206:209], v154
	ds_read_b128 v[210:213], v154 offset:1024
	ds_read_b128 v[214:217], v154 offset:2048
	ds_read_b128 v[222:225], v154 offset:3072
	global_load_lds_dwordx4 v[218:219], off
	v_lshl_add_u64 v[226:227], s[36:37], 0, v[130:131]
	s_mov_b32 m0, s50
	s_nop 0
	global_load_lds_dwordx4 v[226:227], off
	s_barrier
	s_waitcnt lgkmcnt(0)
	s_setprio 1
	s_waitcnt lgkmcnt(0)
	v_mfma_f32_16x16x32_bf16 v[124:127], v[206:209], v[174:177], v[124:127]
	v_mfma_f32_16x16x32_bf16 v[116:119], v[214:217], v[174:177], v[116:119]
	v_mfma_f32_16x16x32_bf16 v[108:111], v[206:209], v[182:185], v[108:111]
	v_mfma_f32_16x16x32_bf16 v[100:103], v[214:217], v[182:185], v[100:103]
	v_mfma_f32_16x16x32_bf16 v[92:95], v[206:209], v[190:193], v[92:95]
	v_mfma_f32_16x16x32_bf16 v[84:87], v[214:217], v[190:193], v[84:87]
	v_mfma_f32_16x16x32_bf16 v[76:79], v[206:209], v[198:201], v[76:79]
	v_mfma_f32_16x16x32_bf16 v[64:67], v[214:217], v[198:201], v[64:67]
	v_mfma_f32_16x16x32_bf16 v[124:127], v[210:213], v[178:181], v[124:127]
	v_mfma_f32_16x16x32_bf16 v[116:119], v[222:225], v[178:181], v[116:119]
	v_mfma_f32_16x16x32_bf16 v[108:111], v[210:213], v[186:189], v[108:111]
	v_mfma_f32_16x16x32_bf16 v[100:103], v[222:225], v[186:189], v[100:103]
	v_mfma_f32_16x16x32_bf16 v[92:95], v[210:213], v[194:197], v[92:95]
	v_mfma_f32_16x16x32_bf16 v[84:87], v[222:225], v[194:197], v[84:87]
	v_mfma_f32_16x16x32_bf16 v[76:79], v[210:213], v[202:205], v[76:79]
	v_mfma_f32_16x16x32_bf16 v[64:67], v[222:225], v[202:205], v[64:67]
	s_setprio 0
	s_add_u32 s62, s62, s61
	s_addc_u32 s63, s63, 0
	s_mov_b32 m0, s25
	v_lshl_add_u64 v[228:229], s[62:63], 0, v[136:137]
	s_barrier
	ds_read_b128 v[174:177], v153 offset:16384
	ds_read_b128 v[178:181], v153 offset:17408
	ds_read_b128 v[182:185], v153 offset:18432
	ds_read_b128 v[186:189], v153 offset:19456
	ds_read_b128 v[190:193], v153 offset:20480
	ds_read_b128 v[194:197], v153 offset:21504
	ds_read_b128 v[198:201], v153 offset:22528
	ds_read_b128 v[202:205], v153 offset:23552
	global_load_lds_dwordx4 v[228:229], off
	v_lshl_add_u64 v[230:231], s[62:63], 0, v[132:133]
	s_mov_b32 m0, s41
	s_nop 0
	global_load_lds_dwordx4 v[230:231], off
	s_barrier
	s_waitcnt lgkmcnt(0)
	s_setprio 1
	s_waitcnt lgkmcnt(0)
	v_mfma_f32_16x16x32_bf16 v[56:59], v[158:161], v[174:177], v[56:59]
	v_mfma_f32_16x16x32_bf16 v[48:51], v[166:169], v[174:177], v[48:51]
	v_mfma_f32_16x16x32_bf16 v[40:43], v[158:161], v[182:185], v[40:43]
	v_mfma_f32_16x16x32_bf16 v[32:35], v[166:169], v[182:185], v[32:35]
	v_mfma_f32_16x16x32_bf16 v[24:27], v[158:161], v[190:193], v[24:27]
	v_mfma_f32_16x16x32_bf16 v[16:19], v[166:169], v[190:193], v[16:19]
	v_mfma_f32_16x16x32_bf16 v[8:11], v[158:161], v[198:201], v[8:11]
	v_mfma_f32_16x16x32_bf16 v[0:3], v[166:169], v[198:201], v[0:3]
	v_mfma_f32_16x16x32_bf16 v[56:59], v[162:165], v[178:181], v[56:59]
	v_mfma_f32_16x16x32_bf16 v[48:51], v[170:173], v[178:181], v[48:51]
	v_mfma_f32_16x16x32_bf16 v[40:43], v[162:165], v[186:189], v[40:43]
	v_mfma_f32_16x16x32_bf16 v[32:35], v[170:173], v[186:189], v[32:35]
	v_mfma_f32_16x16x32_bf16 v[24:27], v[162:165], v[194:197], v[24:27]
	v_mfma_f32_16x16x32_bf16 v[16:19], v[170:173], v[194:197], v[16:19]
	v_mfma_f32_16x16x32_bf16 v[8:11], v[162:165], v[202:205], v[8:11]
	v_mfma_f32_16x16x32_bf16 v[0:3], v[170:173], v[202:205], v[0:3]
	s_setprio 0
	s_barrier
	s_add_u32 s64, s36, 0x40000
	s_addc_u32 s65, s37, 0
	s_mov_b32 m0, s55
	v_lshl_add_u64 v[158:159], s[64:65], 0, v[134:135]
	global_load_lds_dwordx4 v[158:159], off
	v_lshl_add_u64 v[158:159], s[64:65], 0, v[130:131]
	s_mov_b32 m0, s56
	s_nop 0
	global_load_lds_dwordx4 v[158:159], off
	s_waitcnt vmcnt(6)
	s_barrier
	s_setprio 1
	v_mfma_f32_16x16x32_bf16 v[68:71], v[206:209], v[174:177], v[68:71]
	v_mfma_f32_16x16x32_bf16 v[52:55], v[214:217], v[174:177], v[52:55]
	v_mfma_f32_16x16x32_bf16 v[44:47], v[206:209], v[182:185], v[44:47]
	v_mfma_f32_16x16x32_bf16 v[36:39], v[214:217], v[182:185], v[36:39]
	v_mfma_f32_16x16x32_bf16 v[28:31], v[206:209], v[190:193], v[28:31]
	v_mfma_f32_16x16x32_bf16 v[20:23], v[214:217], v[190:193], v[20:23]
	v_mfma_f32_16x16x32_bf16 v[12:15], v[206:209], v[198:201], v[12:15]
	v_mfma_f32_16x16x32_bf16 v[4:7], v[214:217], v[198:201], v[4:7]
	v_mfma_f32_16x16x32_bf16 v[68:71], v[210:213], v[178:181], v[68:71]
	v_mfma_f32_16x16x32_bf16 v[52:55], v[222:225], v[178:181], v[52:55]
	v_mfma_f32_16x16x32_bf16 v[44:47], v[210:213], v[186:189], v[44:47]
	v_mfma_f32_16x16x32_bf16 v[36:39], v[222:225], v[186:189], v[36:39]
	v_mfma_f32_16x16x32_bf16 v[28:31], v[210:213], v[194:197], v[28:31]
	v_mfma_f32_16x16x32_bf16 v[20:23], v[222:225], v[194:197], v[20:23]
	v_mfma_f32_16x16x32_bf16 v[12:15], v[210:213], v[202:205], v[12:15]
	v_mfma_f32_16x16x32_bf16 v[4:7], v[222:225], v[202:205], v[4:7]
	s_setprio 0
	s_barrier
	ds_read_b128 v[158:161], v155
	ds_read_b128 v[162:165], v155 offset:1024
	ds_read_b128 v[166:169], v155 offset:2048
	ds_read_b128 v[170:173], v155 offset:3072
	s_add_u32 s62, s62, 0x40000
	s_addc_u32 s63, s63, 0
	s_mov_b32 m0, s42
	v_lshl_add_u64 v[206:207], s[62:63], 0, v[136:137]
	ds_read_b128 v[174:177], v153 offset:32768
	ds_read_b128 v[178:181], v153 offset:33792
	ds_read_b128 v[182:185], v153 offset:34816
	ds_read_b128 v[186:189], v153 offset:35840
	ds_read_b128 v[190:193], v153 offset:36864
	ds_read_b128 v[194:197], v153 offset:37888
	ds_read_b128 v[198:201], v153 offset:38912
	ds_read_b128 v[202:205], v153 offset:39936
	global_load_lds_dwordx4 v[206:207], off
	v_lshl_add_u64 v[206:207], s[62:63], 0, v[132:133]
	s_mov_b32 m0, s43
	s_nop 0
	global_load_lds_dwordx4 v[206:207], off
	s_waitcnt lgkmcnt(8)
	s_barrier
	s_waitcnt lgkmcnt(0)
	s_setprio 1
	s_waitcnt lgkmcnt(0)
	v_mfma_f32_16x16x32_bf16 v[120:123], v[158:161], v[174:177], v[120:123]
	v_mfma_f32_16x16x32_bf16 v[112:115], v[166:169], v[174:177], v[112:115]
	v_mfma_f32_16x16x32_bf16 v[104:107], v[158:161], v[182:185], v[104:107]
	v_mfma_f32_16x16x32_bf16 v[96:99], v[166:169], v[182:185], v[96:99]
	v_mfma_f32_16x16x32_bf16 v[88:91], v[158:161], v[190:193], v[88:91]
	v_mfma_f32_16x16x32_bf16 v[80:83], v[166:169], v[190:193], v[80:83]
	v_mfma_f32_16x16x32_bf16 v[72:75], v[158:161], v[198:201], v[72:75]
	v_mfma_f32_16x16x32_bf16 v[60:63], v[166:169], v[198:201], v[60:63]
	v_mfma_f32_16x16x32_bf16 v[120:123], v[162:165], v[178:181], v[120:123]
	v_mfma_f32_16x16x32_bf16 v[112:115], v[170:173], v[178:181], v[112:115]
	v_mfma_f32_16x16x32_bf16 v[104:107], v[162:165], v[186:189], v[104:107]
	v_mfma_f32_16x16x32_bf16 v[96:99], v[170:173], v[186:189], v[96:99]
	v_mfma_f32_16x16x32_bf16 v[88:91], v[162:165], v[194:197], v[88:91]
	v_mfma_f32_16x16x32_bf16 v[80:83], v[170:173], v[194:197], v[80:83]
	v_mfma_f32_16x16x32_bf16 v[72:75], v[162:165], v[202:205], v[72:75]
	v_mfma_f32_16x16x32_bf16 v[60:63], v[170:173], v[202:205], v[60:63]
	s_setprio 0
	s_barrier
	s_mov_b32 m0, s57
	v_lshl_add_u64 v[218:219], v[218:219], 0, s[6:7]
	ds_read_b128 v[206:209], v156
	ds_read_b128 v[210:213], v156 offset:1024
	ds_read_b128 v[214:217], v156 offset:2048
	ds_read_b128 v[222:225], v156 offset:3072
	global_load_lds_dwordx4 v[218:219], off
	v_lshl_add_u64 v[218:219], v[226:227], 0, s[6:7]
	s_mov_b32 m0, s58
	s_nop 0
	global_load_lds_dwordx4 v[218:219], off
	s_barrier
	s_waitcnt lgkmcnt(0)
	s_setprio 1
	s_waitcnt lgkmcnt(0)
	v_mfma_f32_16x16x32_bf16 v[124:127], v[206:209], v[174:177], v[124:127]
	v_mfma_f32_16x16x32_bf16 v[116:119], v[214:217], v[174:177], v[116:119]
	v_mfma_f32_16x16x32_bf16 v[108:111], v[206:209], v[182:185], v[108:111]
	v_mfma_f32_16x16x32_bf16 v[100:103], v[214:217], v[182:185], v[100:103]
	v_mfma_f32_16x16x32_bf16 v[92:95], v[206:209], v[190:193], v[92:95]
	v_mfma_f32_16x16x32_bf16 v[84:87], v[214:217], v[190:193], v[84:87]
	v_mfma_f32_16x16x32_bf16 v[76:79], v[206:209], v[198:201], v[76:79]
	v_mfma_f32_16x16x32_bf16 v[64:67], v[214:217], v[198:201], v[64:67]
	v_mfma_f32_16x16x32_bf16 v[124:127], v[210:213], v[178:181], v[124:127]
	v_mfma_f32_16x16x32_bf16 v[116:119], v[222:225], v[178:181], v[116:119]
	v_mfma_f32_16x16x32_bf16 v[108:111], v[210:213], v[186:189], v[108:111]
	v_mfma_f32_16x16x32_bf16 v[100:103], v[222:225], v[186:189], v[100:103]
	v_mfma_f32_16x16x32_bf16 v[92:95], v[210:213], v[194:197], v[92:95]
	v_mfma_f32_16x16x32_bf16 v[84:87], v[222:225], v[194:197], v[84:87]
	v_mfma_f32_16x16x32_bf16 v[76:79], v[210:213], v[202:205], v[76:79]
	v_mfma_f32_16x16x32_bf16 v[64:67], v[222:225], v[202:205], v[64:67]
	s_setprio 0
	s_mov_b32 m0, s44
	v_lshl_add_u64 v[218:219], v[228:229], 0, s[6:7]
	s_barrier
	ds_read_b128 v[174:177], v153 offset:49152
	ds_read_b128 v[178:181], v153 offset:50176
	ds_read_b128 v[182:185], v153 offset:51200
	ds_read_b128 v[186:189], v153 offset:52224
	ds_read_b128 v[190:193], v153 offset:53248
	ds_read_b128 v[194:197], v153 offset:54272
	ds_read_b128 v[198:201], v153 offset:55296
	ds_read_b128 v[202:205], v153 offset:56320
	global_load_lds_dwordx4 v[218:219], off
	v_lshl_add_u64 v[218:219], v[230:231], 0, s[6:7]
	s_mov_b32 m0, s45
	s_nop 0
	global_load_lds_dwordx4 v[218:219], off
	s_barrier
;     ...
;         G_PAIR(0, 1);
; #pragma unroll 1
;         for (int t = 2; t < nt; t += 2) G_PAIR(t, 0);
;         p.epi(acc, cur, wr, wc, fr, fq);
;         if (!has_next) break;
;         cur = nxt; cA = nA; cB = nB; cA2 = nA2; cB2 = nB2; ++ui;
;     __device__ __forceinline__ void epi(const f32x4 (&acc)[2][2][4][2], const Unit& u, int wr, int wc, int fr, int fq) const {
;     ...
;         for (int ai = 0; ai < 2; ++ai)
; #pragma unroll
;             for (int m = 0; m < 4; ++m) {
;                 const int row = row0 + ai * 128 + m * 16; const float rs = rs_lds[((u.pm >> 3) & 1) * 256 + (row & 255)];
;                 const float rs2 = rs * -1.4426950408889634f, rsq = rs * rs;
;                 f32x2 v[4];
; #pragma unroll
;                 for (int n = 0; n < 2; ++n)
; #pragma unroll
;                     for (int jp = 0; jp < 2; ++jp) {
;                         const f32x2 gg = (f32x2){acc[ai][0][m][n][2 * jp], acc[ai][0][m][n][2 * jp + 1]}, uu = (f32x2){acc[ai][1][m][n][2 * jp], acc[ai][1][m][n][2 * jp + 1]};
;                         const f32x2 t = gg * rs2; f32x2 e; e.x = __builtin_amdgcn_exp2f(t.x); e.y = __builtin_amdgcn_exp2f(t.y);
;                         const f32x2 d = e + 1.0f; f32x2 r; r.x = __builtin_amdgcn_rcpf(d.x); r.y = __builtin_amdgcn_rcpf(d.y);
;                         v[n * 2 + jp] = (gg * uu) * (r * rsq);
	s_waitcnt lgkmcnt(0)
	s_setprio 1
	s_waitcnt lgkmcnt(0)
	v_mfma_f32_16x16x32_bf16 v[56:59], v[158:161], v[174:177], v[56:59]
	v_mfma_f32_16x16x32_bf16 v[48:51], v[166:169], v[174:177], v[48:51]
	v_mfma_f32_16x16x32_bf16 v[40:43], v[158:161], v[182:185], v[40:43]
	v_mfma_f32_16x16x32_bf16 v[32:35], v[166:169], v[182:185], v[32:35]
	v_mfma_f32_16x16x32_bf16 v[24:27], v[158:161], v[190:193], v[24:27]
	v_mfma_f32_16x16x32_bf16 v[16:19], v[166:169], v[190:193], v[16:19]
	v_mfma_f32_16x16x32_bf16 v[8:11], v[158:161], v[198:201], v[8:11]
	v_mfma_f32_16x16x32_bf16 v[0:3], v[166:169], v[198:201], v[0:3]
	v_mfma_f32_16x16x32_bf16 v[56:59], v[162:165], v[178:181], v[56:59]
	v_mfma_f32_16x16x32_bf16 v[48:51], v[170:173], v[178:181], v[48:51]
	v_mfma_f32_16x16x32_bf16 v[40:43], v[162:165], v[186:189], v[40:43]
	v_mfma_f32_16x16x32_bf16 v[32:35], v[170:173], v[186:189], v[32:35]
	v_mfma_f32_16x16x32_bf16 v[24:27], v[162:165], v[194:197], v[24:27]
	v_mfma_f32_16x16x32_bf16 v[16:19], v[170:173], v[194:197], v[16:19]
	v_mfma_f32_16x16x32_bf16 v[8:11], v[162:165], v[202:205], v[8:11]
	v_mfma_f32_16x16x32_bf16 v[0:3], v[170:173], v[202:205], v[0:3]
	s_setprio 0
	s_barrier
	s_add_u32 s36, s36, 0x40080
	s_addc_u32 s37, s37, 0
	s_mov_b32 m0, s59
	v_lshl_add_u64 v[158:159], s[36:37], 0, v[134:135]
	global_load_lds_dwordx4 v[158:159], off
	v_lshl_add_u64 v[158:159], s[36:37], 0, v[130:131]
	s_mov_b32 m0, s17
	s_nop 0
	global_load_lds_dwordx4 v[158:159], off
	s_waitcnt vmcnt(6)
	s_barrier
	s_setprio 1
	v_mfma_f32_16x16x32_bf16 v[68:71], v[206:209], v[174:177], v[68:71]
	v_mfma_f32_16x16x32_bf16 v[52:55], v[214:217], v[174:177], v[52:55]
	v_mfma_f32_16x16x32_bf16 v[44:47], v[206:209], v[182:185], v[44:47]
	v_mfma_f32_16x16x32_bf16 v[36:39], v[214:217], v[182:185], v[36:39]
	v_mfma_f32_16x16x32_bf16 v[28:31], v[206:209], v[190:193], v[28:31]
	v_mfma_f32_16x16x32_bf16 v[20:23], v[214:217], v[190:193], v[20:23]
	v_mfma_f32_16x16x32_bf16 v[12:15], v[206:209], v[198:201], v[12:15]
	v_mfma_f32_16x16x32_bf16 v[4:7], v[214:217], v[198:201], v[4:7]
	v_mfma_f32_16x16x32_bf16 v[68:71], v[210:213], v[178:181], v[68:71]
	v_mfma_f32_16x16x32_bf16 v[52:55], v[222:225], v[178:181], v[52:55]
	v_mfma_f32_16x16x32_bf16 v[44:47], v[210:213], v[186:189], v[44:47]
	v_mfma_f32_16x16x32_bf16 v[36:39], v[222:225], v[186:189], v[36:39]
	v_mfma_f32_16x16x32_bf16 v[28:31], v[210:213], v[194:197], v[28:31]
	v_mfma_f32_16x16x32_bf16 v[20:23], v[222:225], v[194:197], v[20:23]
	v_mfma_f32_16x16x32_bf16 v[12:15], v[210:213], v[202:205], v[12:15]
	v_mfma_f32_16x16x32_bf16 v[4:7], v[222:225], v[202:205], v[4:7]
	s_setprio 0
	s_add_i32 s19, s19, 2
	s_add_u32 s34, s34, 0x100
	s_addc_u32 s35, s35, 0
	s_cmp_gt_u32 s19, 13
	s_barrier
	s_cbranch_scc0 .LBB0_232
	s_lshl_b32 s17, s24, 7
	s_and_b32 s17, s17, 0x400
	s_add_i32 s17, s17, 0
	s_add_i32 s17, s17, 0x20000
	v_lshl_add_u32 v142, v151, 2, s17
	ds_read_b32 v143, v142
	v_lshl_add_u32 v142, s24, 8, v129
	v_lshl_or_b32 v144, s60, 7, v150
	v_ashrrev_i32_e32 v145, 31, v144
	s_and_b64 vcc, exec, s[14:15]
	s_waitcnt lgkmcnt(0)
	v_mul_f32_e32 v158, 0xbfb8aa3b, v143
	v_pk_mul_f32 v[160:161], v[120:121], v[158:159] op_sel_hi:[1,0]
	v_pk_mul_f32 v[164:165], v[122:123], v[158:159] op_sel_hi:[1,0]
	v_exp_f32_e32 v160, v160
	v_exp_f32_e32 v161, v161
	v_exp_f32_e32 v164, v164
	v_exp_f32_e32 v165, v165
	v_pk_mul_f32 v[122:123], v[122:123], v[126:127]
	v_pk_add_f32 v[160:161], v[160:161], 1.0 op_sel_hi:[1,0]
	v_mul_f32_e32 v162, v143, v143
	v_rcp_f32_e32 v160, v160
	v_rcp_f32_e32 v161, v161
	v_pk_add_f32 v[126:127], v[164:165], 1.0 op_sel_hi:[1,0]
	v_pk_mul_f32 v[120:121], v[120:121], v[124:125]
	v_rcp_f32_e32 v126, v126
	v_rcp_f32_e32 v127, v127
	v_pk_mul_f32 v[124:125], v[162:163], v[160:161] op_sel_hi:[0,1]
	v_pk_mul_f32 v[160:161], v[112:113], v[158:159] op_sel_hi:[1,0]
	v_pk_mul_f32 v[120:121], v[120:121], v[124:125]
	v_exp_f32_e32 v160, v160
	v_exp_f32_e32 v161, v161
	v_pk_mul_f32 v[124:125], v[162:163], v[126:127] op_sel_hi:[0,1]
	v_pk_mul_f32 v[126:127], v[114:115], v[158:159] op_sel_hi:[1,0]
	v_pk_mul_f32 v[122:123], v[122:123], v[124:125]
	v_exp_f32_e32 v126, v126
	v_exp_f32_e32 v127, v127
	v_pk_add_f32 v[124:125], v[160:161], 1.0 op_sel_hi:[1,0]
	v_pk_mul_f32 v[114:115], v[114:115], v[118:119]
	v_rcp_f32_e32 v124, v124
	v_rcp_f32_e32 v125, v125
	v_pk_add_f32 v[118:119], v[126:127], 1.0 op_sel_hi:[1,0]
	v_pk_mul_f32 v[112:113], v[112:113], v[116:117]
	v_rcp_f32_e32 v118, v118
	v_rcp_f32_e32 v119, v119
	v_pk_mul_f32 v[116:117], v[162:163], v[124:125] op_sel_hi:[0,1]
	v_pk_mul_f32 v[112:113], v[112:113], v[116:117]
	s_mov_b32 s60, s16
	v_pk_mul_f32 v[116:117], v[162:163], v[118:119] op_sel_hi:[0,1]
	v_pk_mul_f32 v[114:115], v[114:115], v[116:117]
	v_cvt_pk_bf16_f32 v116, v120, v121
	v_cvt_pk_bf16_f32 v117, v122, v123
	v_cvt_pk_bf16_f32 v118, v112, v113
	v_bitop3_b32 v112, v142, s52, 16 bitop3:0xc8
	v_lshl_add_u32 v112, v112, 2, s17
	v_cvt_pk_bf16_f32 v119, v114, v115
	ds_read_b32 v123, v112
	v_mov_b64_e32 v[112:113], s[2:3]
	v_mad_i64_i32 v[120:121], s[26:27], v142, s51, v[112:113]
	v_lshlrev_b64 v[114:115], 1, v[144:145]
	s_waitcnt lgkmcnt(0)
; __device__ __forceinline__ unsigned pk2(float lo, float hi) { unsigned r; asm volatile("v_cvt_pk_bf16_f32 %0, %1, %2" : "=v"(r) : "v"(lo), "v"(hi)); return r; }
; __device__ __forceinline__ unsigned pk2(float lo, float hi) { return f2bf(lo) | (f2bf(hi) << 16); }
;     __device__ __forceinline__ void epi(const f32x4 (&acc)[2][2][4][2], const Unit& u, int wr, int wc, int fr, int fq) const {
;     ...
;         for (int ai = 0; ai < 2; ++ai)
; #pragma unroll
;             for (int m = 0; m < 4; ++m) {
;                 const int row = row0 + ai * 128 + m * 16; const float rs = rs_lds[((u.pm >> 3) & 1) * 256 + (row & 255)];
;                 const float rs2 = rs * -1.4426950408889634f, rsq = rs * rs;
;                 f32x2 v[4];
; #pragma unroll
;                 for (int n = 0; n < 2; ++n)
; #pragma unroll
;                     for (int jp = 0; jp < 2; ++jp) {
;                         const f32x2 gg = (f32x2){acc[ai][0][m][n][2 * jp], acc[ai][0][m][n][2 * jp + 1]}, uu = (f32x2){acc[ai][1][m][n][2 * jp], acc[ai][1][m][n][2 * jp + 1]};
;                         const f32x2 t = gg * rs2; f32x2 e; e.x = __builtin_amdgcn_exp2f(t.x); e.y = __builtin_amdgcn_exp2f(t.y);
;                         const f32x2 d = e + 1.0f; f32x2 r; r.x = __builtin_amdgcn_rcpf(d.x); r.y = __builtin_amdgcn_rcpf(d.y);
;                         v[n * 2 + jp] = (gg * uu) * (r * rsq);
;                     }
;                 u32x4 w; w.x = pk2(v[0].x, v[0].y); w.y = pk2(v[1].x, v[1].y); w.z = pk2(v[2].x, v[2].y); w.w = pk2(v[3].x, v[3].y);
;                 *(u32x4*)(H + (size_t)row * FF + col0) = w;
	v_mul_f32_e32 v122, 0xbfb8aa3b, v123
	v_pk_mul_f32 v[124:125], v[104:105], v[122:123] op_sel_hi:[1,0]
	v_lshl_add_u64 v[120:121], v[120:121], 0, v[114:115]
	v_exp_f32_e32 v124, v124
	v_exp_f32_e32 v125, v125
	global_store_dwordx4 v[120:121], v[116:119], off
	v_pk_mul_f32 v[120:121], v[106:107], v[122:123] op_sel_hi:[1,0]
	v_pk_mul_f32 v[106:107], v[106:107], v[110:111]
	v_exp_f32_e32 v120, v120
	v_exp_f32_e32 v121, v121
	v_pk_add_f32 v[118:119], v[124:125], 1.0 op_sel_hi:[1,0]
	v_mul_f32_e32 v116, v123, v123
	v_rcp_f32_e32 v118, v118
	v_rcp_f32_e32 v119, v119
	v_pk_add_f32 v[110:111], v[120:121], 1.0 op_sel_hi:[1,0]
	v_pk_mul_f32 v[104:105], v[104:105], v[108:109]
	v_rcp_f32_e32 v110, v110
	v_rcp_f32_e32 v111, v111
	v_pk_mul_f32 v[108:109], v[116:117], v[118:119] op_sel_hi:[0,1]
	v_pk_mul_f32 v[118:119], v[96:97], v[122:123] op_sel_hi:[1,0]
	v_pk_mul_f32 v[104:105], v[104:105], v[108:109]
	v_exp_f32_e32 v118, v118
	v_exp_f32_e32 v119, v119
	v_pk_mul_f32 v[108:109], v[116:117], v[110:111] op_sel_hi:[0,1]
	v_pk_mul_f32 v[110:111], v[98:99], v[122:123] op_sel_hi:[1,0]
	v_pk_mul_f32 v[106:107], v[106:107], v[108:109]
	v_exp_f32_e32 v110, v110
	v_exp_f32_e32 v111, v111
	v_pk_add_f32 v[108:109], v[118:119], 1.0 op_sel_hi:[1,0]
	v_pk_mul_f32 v[98:99], v[98:99], v[102:103]
	v_rcp_f32_e32 v108, v108
	v_rcp_f32_e32 v109, v109
	v_pk_add_f32 v[102:103], v[110:111], 1.0 op_sel_hi:[1,0]
	v_pk_mul_f32 v[96:97], v[96:97], v[100:101]
	v_rcp_f32_e32 v102, v102
	v_rcp_f32_e32 v103, v103
	v_pk_mul_f32 v[100:101], v[116:117], v[108:109] op_sel_hi:[0,1]
	v_pk_mul_f32 v[100:101], v[96:97], v[100:101]
	s_mov_b32 s24, s18
	v_pk_mul_f32 v[96:97], v[116:117], v[102:103] op_sel_hi:[0,1]
	v_pk_mul_f32 v[102:103], v[98:99], v[96:97]
	v_cvt_pk_bf16_f32 v96, v104, v105
	v_cvt_pk_bf16_f32 v97, v106, v107
	v_cvt_pk_bf16_f32 v98, v100, v101
	v_bitop3_b32 v100, v142, s53, 32 bitop3:0xc8
	v_lshl_add_u32 v100, v100, 2, s17
	v_cvt_pk_bf16_f32 v99, v102, v103
	ds_read_b32 v103, v100
	v_or_b32_e32 v100, 16, v142
	v_mad_i64_i32 v[100:101], s[26:27], v100, s51, v[112:113]
	v_lshl_add_u64 v[100:101], v[100:101], 0, v[114:115]
	s_waitcnt lgkmcnt(0)
	v_mul_f32_e32 v102, 0xbfb8aa3b, v103
	v_pk_mul_f32 v[104:105], v[88:89], v[102:103] op_sel_hi:[1,0]
	global_store_dwordx4 v[100:101], v[96:99], off
	v_exp_f32_e32 v104, v104
	v_exp_f32_e32 v105, v105
	v_pk_mul_f32 v[100:101], v[90:91], v[102:103] op_sel_hi:[1,0]
	v_pk_mul_f32 v[90:91], v[90:91], v[94:95]
	v_exp_f32_e32 v100, v100
	v_exp_f32_e32 v101, v101
	v_pk_add_f32 v[98:99], v[104:105], 1.0 op_sel_hi:[1,0]
	v_mul_f32_e32 v96, v103, v103
	v_rcp_f32_e32 v98, v98
	v_rcp_f32_e32 v99, v99
	v_pk_add_f32 v[94:95], v[100:101], 1.0 op_sel_hi:[1,0]
	v_pk_mul_f32 v[88:89], v[88:89], v[92:93]
	v_rcp_f32_e32 v94, v94
	v_rcp_f32_e32 v95, v95
	v_pk_mul_f32 v[92:93], v[96:97], v[98:99] op_sel_hi:[0,1]
	v_pk_mul_f32 v[98:99], v[80:81], v[102:103] op_sel_hi:[1,0]
	v_pk_mul_f32 v[88:89], v[88:89], v[92:93]
	v_exp_f32_e32 v98, v98
	v_exp_f32_e32 v99, v99
	v_pk_mul_f32 v[92:93], v[96:97], v[94:95] op_sel_hi:[0,1]
	v_pk_mul_f32 v[94:95], v[82:83], v[102:103] op_sel_hi:[1,0]
	v_pk_mul_f32 v[90:91], v[90:91], v[92:93]
	v_exp_f32_e32 v94, v94
	v_exp_f32_e32 v95, v95
	v_pk_add_f32 v[92:93], v[98:99], 1.0 op_sel_hi:[1,0]
	v_pk_mul_f32 v[82:83], v[82:83], v[86:87]
	v_rcp_f32_e32 v92, v92
	v_rcp_f32_e32 v93, v93
	v_pk_add_f32 v[86:87], v[94:95], 1.0 op_sel_hi:[1,0]
	v_pk_mul_f32 v[80:81], v[80:81], v[84:85]
	v_rcp_f32_e32 v86, v86
	v_rcp_f32_e32 v87, v87
	v_pk_mul_f32 v[84:85], v[96:97], v[92:93] op_sel_hi:[0,1]
	v_pk_mul_f32 v[84:85], v[80:81], v[84:85]
	s_mov_b64 s[28:29], s[22:23]
	v_pk_mul_f32 v[80:81], v[96:97], v[86:87] op_sel_hi:[0,1]
	v_pk_mul_f32 v[86:87], v[82:83], v[80:81]
	v_cvt_pk_bf16_f32 v80, v88, v89
	v_cvt_pk_bf16_f32 v81, v90, v91
	v_cvt_pk_bf16_f32 v82, v84, v85
	v_bitop3_b32 v84, v142, s54, 48 bitop3:0xc8
	v_lshl_add_u32 v84, v84, 2, s17
	v_cvt_pk_bf16_f32 v83, v86, v87
	ds_read_b32 v87, v84
	v_or_b32_e32 v84, 32, v142
	v_mad_i64_i32 v[84:85], s[26:27], v84, s51, v[112:113]
	v_lshl_add_u64 v[84:85], v[84:85], 0, v[114:115]
	s_waitcnt lgkmcnt(0)
	v_mul_f32_e32 v86, 0xbfb8aa3b, v87
	v_pk_mul_f32 v[88:89], v[72:73], v[86:87] op_sel_hi:[1,0]
	global_store_dwordx4 v[84:85], v[80:83], off
	v_exp_f32_e32 v88, v88
	v_exp_f32_e32 v89, v89
	v_pk_mul_f32 v[84:85], v[74:75], v[86:87] op_sel_hi:[1,0]
	v_pk_mul_f32 v[74:75], v[74:75], v[78:79]
	v_exp_f32_e32 v84, v84
	v_exp_f32_e32 v85, v85
	v_pk_add_f32 v[82:83], v[88:89], 1.0 op_sel_hi:[1,0]
	v_mul_f32_e32 v80, v87, v87
	v_rcp_f32_e32 v82, v82
	v_rcp_f32_e32 v83, v83
	v_pk_add_f32 v[78:79], v[84:85], 1.0 op_sel_hi:[1,0]
	v_pk_mul_f32 v[72:73], v[72:73], v[76:77]
	v_rcp_f32_e32 v78, v78
	v_rcp_f32_e32 v79, v79
	v_pk_mul_f32 v[76:77], v[80:81], v[82:83] op_sel_hi:[0,1]
	v_pk_mul_f32 v[82:83], v[60:61], v[86:87] op_sel_hi:[1,0]
	v_pk_mul_f32 v[72:73], v[72:73], v[76:77]
	v_exp_f32_e32 v82, v82
	v_exp_f32_e32 v83, v83
	v_pk_mul_f32 v[76:77], v[80:81], v[78:79] op_sel_hi:[0,1]
	v_pk_mul_f32 v[78:79], v[62:63], v[86:87] op_sel_hi:[1,0]
	v_pk_mul_f32 v[74:75], v[74:75], v[76:77]
	v_exp_f32_e32 v78, v78
	v_exp_f32_e32 v79, v79
	v_pk_add_f32 v[76:77], v[82:83], 1.0 op_sel_hi:[1,0]
	v_pk_mul_f32 v[62:63], v[62:63], v[66:67]
	v_rcp_f32_e32 v76, v76
	v_rcp_f32_e32 v77, v77
	v_pk_add_f32 v[66:67], v[78:79], 1.0 op_sel_hi:[1,0]
	v_pk_mul_f32 v[60:61], v[60:61], v[64:65]
	v_rcp_f32_e32 v66, v66
	v_rcp_f32_e32 v67, v67
	v_pk_mul_f32 v[64:65], v[80:81], v[76:77] op_sel_hi:[0,1]
	v_pk_mul_f32 v[64:65], v[60:61], v[64:65]
	v_pk_mul_f32 v[60:61], v[80:81], v[66:67] op_sel_hi:[0,1]
	v_pk_mul_f32 v[66:67], v[62:63], v[60:61]
	v_cvt_pk_bf16_f32 v60, v72, v73
	v_cvt_pk_bf16_f32 v61, v74, v75
	v_cvt_pk_bf16_f32 v62, v64, v65
	s_nop 0
	v_cvt_pk_bf16_f32 v63, v66, v67
	v_add_u32_e32 v67, 0x80, v142
	v_and_b32_e32 v64, 0xcf, v67
	v_lshl_add_u32 v64, v64, 2, s17
	ds_read_b32 v74, v64
	v_or_b32_e32 v64, 48, v142
	v_mad_i64_i32 v[64:65], s[26:27], v64, s51, v[112:113]
	v_lshl_add_u64 v[64:65], v[64:65], 0, v[114:115]
	s_waitcnt lgkmcnt(0)
; __device__ __forceinline__ unsigned pk2(float lo, float hi) { unsigned r; asm volatile("v_cvt_pk_bf16_f32 %0, %1, %2" : "=v"(r) : "v"(lo), "v"(hi)); return r; }
; __device__ __forceinline__ unsigned pk2(float lo, float hi) { return f2bf(lo) | (f2bf(hi) << 16); }
;     __device__ __forceinline__ void epi(const f32x4 (&acc)[2][2][4][2], const Unit& u, int wr, int wc, int fr, int fq) const {
;     ...
;         for (int ai = 0; ai < 2; ++ai)
; #pragma unroll
;             for (int m = 0; m < 4; ++m) {
;                 const int row = row0 + ai * 128 + m * 16; const float rs = rs_lds[((u.pm >> 3) & 1) * 256 + (row & 255)];
;                 const float rs2 = rs * -1.4426950408889634f, rsq = rs * rs;
;                 f32x2 v[4];
; #pragma unroll
;                 for (int n = 0; n < 2; ++n)
; #pragma unroll
;                     for (int jp = 0; jp < 2; ++jp) {
;                         const f32x2 gg = (f32x2){acc[ai][0][m][n][2 * jp], acc[ai][0][m][n][2 * jp + 1]}, uu = (f32x2){acc[ai][1][m][n][2 * jp], acc[ai][1][m][n][2 * jp + 1]};
;                         const f32x2 t = gg * rs2; f32x2 e; e.x = __builtin_amdgcn_exp2f(t.x); e.y = __builtin_amdgcn_exp2f(t.y);
;                         const f32x2 d = e + 1.0f; f32x2 r; r.x = __builtin_amdgcn_rcpf(d.x); r.y = __builtin_amdgcn_rcpf(d.y);
;                         v[n * 2 + jp] = (gg * uu) * (r * rsq);
;                     }
;                 u32x4 w; w.x = pk2(v[0].x, v[0].y); w.y = pk2(v[1].x, v[1].y); w.z = pk2(v[2].x, v[2].y); w.w = pk2(v[3].x, v[3].y);
;                 *(u32x4*)(H + (size_t)row * FF + col0) = w;
	v_mul_f32_e32 v66, 0xbfb8aa3b, v74
	v_pk_mul_f32 v[72:73], v[56:57], v[66:67] op_sel_hi:[1,0]
	global_store_dwordx4 v[64:65], v[60:63], off
	v_exp_f32_e32 v72, v72
	v_exp_f32_e32 v73, v73
	v_pk_mul_f32 v[64:65], v[58:59], v[66:67] op_sel_hi:[1,0]
	v_mul_f32_e32 v60, v74, v74
	v_exp_f32_e32 v64, v64
	v_exp_f32_e32 v65, v65
	v_pk_add_f32 v[62:63], v[72:73], 1.0 op_sel_hi:[1,0]
	v_pk_mul_f32 v[56:57], v[56:57], v[68:69]
	v_rcp_f32_e32 v62, v62
	v_rcp_f32_e32 v63, v63
	v_pk_add_f32 v[64:65], v[64:65], 1.0 op_sel_hi:[1,0]
	v_pk_mul_f32 v[68:69], v[48:49], v[66:67] op_sel_hi:[1,0]
	v_rcp_f32_e32 v64, v64
	v_rcp_f32_e32 v65, v65
	v_pk_mul_f32 v[62:63], v[60:61], v[62:63] op_sel_hi:[0,1]
	v_exp_f32_e32 v68, v68
	v_exp_f32_e32 v69, v69
	v_pk_mul_f32 v[56:57], v[56:57], v[62:63]
	v_pk_mul_f32 v[62:63], v[60:61], v[64:65] op_sel_hi:[0,1]
	v_pk_mul_f32 v[64:65], v[50:51], v[66:67] op_sel_hi:[1,0]
	v_pk_mul_f32 v[58:59], v[58:59], v[70:71]
	v_exp_f32_e32 v64, v64
	v_exp_f32_e32 v65, v65
	v_pk_mul_f32 v[58:59], v[58:59], v[62:63]
	v_pk_add_f32 v[62:63], v[68:69], 1.0 op_sel_hi:[1,0]
	v_pk_mul_f32 v[50:51], v[50:51], v[54:55]
	v_rcp_f32_e32 v62, v62
	v_rcp_f32_e32 v63, v63
	v_pk_add_f32 v[54:55], v[64:65], 1.0 op_sel_hi:[1,0]
	v_pk_mul_f32 v[48:49], v[48:49], v[52:53]
	v_rcp_f32_e32 v54, v54
	v_rcp_f32_e32 v55, v55
	v_pk_mul_f32 v[52:53], v[60:61], v[62:63] op_sel_hi:[0,1]
	v_pk_mul_f32 v[52:53], v[48:49], v[52:53]
	v_pk_mul_f32 v[48:49], v[60:61], v[54:55] op_sel_hi:[0,1]
	v_pk_mul_f32 v[54:55], v[50:51], v[48:49]
	v_cvt_pk_bf16_f32 v48, v56, v57
	v_cvt_pk_bf16_f32 v49, v58, v59
	v_cvt_pk_bf16_f32 v50, v52, v53
	s_nop 0
	v_cvt_pk_bf16_f32 v51, v54, v55
	v_add_u32_e32 v55, 0x90, v142
	v_and_b32_e32 v52, 0xdf, v55
	v_lshl_add_u32 v52, v52, 2, s17
	ds_read_b32 v58, v52
	v_mad_i64_i32 v[52:53], s[26:27], v67, s51, v[112:113]
	v_lshl_add_u64 v[52:53], v[52:53], 0, v[114:115]
	global_store_dwordx4 v[52:53], v[48:51], off
	s_waitcnt lgkmcnt(0)
	v_mul_f32_e32 v54, 0xbfb8aa3b, v58
	v_pk_mul_f32 v[56:57], v[40:41], v[54:55] op_sel_hi:[1,0]
	v_pk_mul_f32 v[52:53], v[42:43], v[54:55] op_sel_hi:[1,0]
	v_exp_f32_e32 v56, v56
	v_exp_f32_e32 v57, v57
	v_exp_f32_e32 v52, v52
	v_exp_f32_e32 v53, v53
	v_pk_mul_f32 v[42:43], v[42:43], v[46:47]
	v_pk_add_f32 v[50:51], v[56:57], 1.0 op_sel_hi:[1,0]
	v_mul_f32_e32 v48, v58, v58
	v_rcp_f32_e32 v50, v50
	v_rcp_f32_e32 v51, v51
	v_pk_add_f32 v[46:47], v[52:53], 1.0 op_sel_hi:[1,0]
	v_pk_mul_f32 v[40:41], v[40:41], v[44:45]
	v_rcp_f32_e32 v46, v46
	v_rcp_f32_e32 v47, v47
	v_pk_mul_f32 v[44:45], v[48:49], v[50:51] op_sel_hi:[0,1]
	v_pk_mul_f32 v[50:51], v[32:33], v[54:55] op_sel_hi:[1,0]
	v_pk_mul_f32 v[40:41], v[40:41], v[44:45]
	v_exp_f32_e32 v50, v50
	v_exp_f32_e32 v51, v51
	v_pk_mul_f32 v[44:45], v[48:49], v[46:47] op_sel_hi:[0,1]
	v_pk_mul_f32 v[46:47], v[34:35], v[54:55] op_sel_hi:[1,0]
	v_pk_mul_f32 v[42:43], v[42:43], v[44:45]
	v_exp_f32_e32 v46, v46
	v_exp_f32_e32 v47, v47
	v_pk_add_f32 v[44:45], v[50:51], 1.0 op_sel_hi:[1,0]
	v_pk_mul_f32 v[34:35], v[34:35], v[38:39]
	v_rcp_f32_e32 v44, v44
	v_rcp_f32_e32 v45, v45
	v_pk_add_f32 v[38:39], v[46:47], 1.0 op_sel_hi:[1,0]
	v_pk_mul_f32 v[32:33], v[32:33], v[36:37]
	v_rcp_f32_e32 v38, v38
	v_rcp_f32_e32 v39, v39
	v_pk_mul_f32 v[36:37], v[48:49], v[44:45] op_sel_hi:[0,1]
	v_pk_mul_f32 v[36:37], v[32:33], v[36:37]
	v_pk_mul_f32 v[32:33], v[48:49], v[38:39] op_sel_hi:[0,1]
	v_pk_mul_f32 v[38:39], v[34:35], v[32:33]
	v_cvt_pk_bf16_f32 v32, v40, v41
	v_cvt_pk_bf16_f32 v33, v42, v43
	v_cvt_pk_bf16_f32 v34, v36, v37
	s_nop 0
	v_cvt_pk_bf16_f32 v35, v38, v39
	v_add_u32_e32 v39, 0xa0, v142
	v_and_b32_e32 v36, 0xef, v39
	v_lshl_add_u32 v36, v36, 2, s17
	ds_read_b32 v42, v36
	v_mad_i64_i32 v[36:37], s[26:27], v55, s51, v[112:113]
	v_lshl_add_u64 v[36:37], v[36:37], 0, v[114:115]
	global_store_dwordx4 v[36:37], v[32:35], off
	s_waitcnt lgkmcnt(0)
; __device__ __forceinline__ unsigned pk2(float lo, float hi) { unsigned r; asm volatile("v_cvt_pk_bf16_f32 %0, %1, %2" : "=v"(r) : "v"(lo), "v"(hi)); return r; }
; __device__ __forceinline__ unsigned pk2(float lo, float hi) { return f2bf(lo) | (f2bf(hi) << 16); }
; #define G_WAIT_V(n) asm volatile("s_waitcnt vmcnt(" #n ")" ::: "memory")
; #define G_BAR __builtin_amdgcn_s_barrier()
;     ...
;         if (!has_next) break;
;         cur = nxt; cA = nA; cB = nB; cA2 = nA2; cB2 = nB2; ++ui;
;     }
;     G_WAIT_V(0);
;     if (wr == 0) G_BAR;
;     G_BAR;
;     __device__ __forceinline__ void epi(const f32x4 (&acc)[2][2][4][2], const Unit& u, int wr, int wc, int fr, int fq) const {
;     ...
;         for (int ai = 0; ai < 2; ++ai)
; #pragma unroll
;             for (int m = 0; m < 4; ++m) {
;                 const int row = row0 + ai * 128 + m * 16; const float rs = rs_lds[((u.pm >> 3) & 1) * 256 + (row & 255)];
;                 const float rs2 = rs * -1.4426950408889634f, rsq = rs * rs;
;                 f32x2 v[4];
; #pragma unroll
;                 for (int n = 0; n < 2; ++n)
; #pragma unroll
;                     for (int jp = 0; jp < 2; ++jp) {
;                         const f32x2 gg = (f32x2){acc[ai][0][m][n][2 * jp], acc[ai][0][m][n][2 * jp + 1]}, uu = (f32x2){acc[ai][1][m][n][2 * jp], acc[ai][1][m][n][2 * jp + 1]};
;                         const f32x2 t = gg * rs2; f32x2 e; e.x = __builtin_amdgcn_exp2f(t.x); e.y = __builtin_amdgcn_exp2f(t.y);
;                         const f32x2 d = e + 1.0f; f32x2 r; r.x = __builtin_amdgcn_rcpf(d.x); r.y = __builtin_amdgcn_rcpf(d.y);
;                         v[n * 2 + jp] = (gg * uu) * (r * rsq);
;                     }
;                 u32x4 w; w.x = pk2(v[0].x, v[0].y); w.y = pk2(v[1].x, v[1].y); w.z = pk2(v[2].x, v[2].y); w.w = pk2(v[3].x, v[3].y);
;                 *(u32x4*)(H + (size_t)row * FF + col0) = w;
	v_mul_f32_e32 v38, 0xbfb8aa3b, v42
	v_pk_mul_f32 v[40:41], v[24:25], v[38:39] op_sel_hi:[1,0]
	v_pk_mul_f32 v[36:37], v[26:27], v[38:39] op_sel_hi:[1,0]
	v_exp_f32_e32 v40, v40
	v_exp_f32_e32 v41, v41
	v_exp_f32_e32 v36, v36
	v_exp_f32_e32 v37, v37
	v_pk_mul_f32 v[26:27], v[26:27], v[30:31]
	v_pk_add_f32 v[34:35], v[40:41], 1.0 op_sel_hi:[1,0]
	v_mul_f32_e32 v32, v42, v42
	v_rcp_f32_e32 v34, v34
	v_rcp_f32_e32 v35, v35
	v_pk_add_f32 v[30:31], v[36:37], 1.0 op_sel_hi:[1,0]
	v_pk_mul_f32 v[24:25], v[24:25], v[28:29]
	v_rcp_f32_e32 v30, v30
	v_rcp_f32_e32 v31, v31
	v_pk_mul_f32 v[28:29], v[32:33], v[34:35] op_sel_hi:[0,1]
	v_pk_mul_f32 v[34:35], v[16:17], v[38:39] op_sel_hi:[1,0]
	v_pk_mul_f32 v[24:25], v[24:25], v[28:29]
	v_exp_f32_e32 v34, v34
	v_exp_f32_e32 v35, v35
	v_pk_mul_f32 v[28:29], v[32:33], v[30:31] op_sel_hi:[0,1]
	v_pk_mul_f32 v[30:31], v[18:19], v[38:39] op_sel_hi:[1,0]
	v_pk_mul_f32 v[26:27], v[26:27], v[28:29]
	v_exp_f32_e32 v30, v30
	v_exp_f32_e32 v31, v31
	v_pk_add_f32 v[28:29], v[34:35], 1.0 op_sel_hi:[1,0]
	v_pk_mul_f32 v[18:19], v[18:19], v[22:23]
	v_rcp_f32_e32 v28, v28
	v_rcp_f32_e32 v29, v29
	v_pk_add_f32 v[22:23], v[30:31], 1.0 op_sel_hi:[1,0]
	v_pk_mul_f32 v[16:17], v[16:17], v[20:21]
	v_rcp_f32_e32 v22, v22
	v_rcp_f32_e32 v23, v23
	v_pk_mul_f32 v[20:21], v[32:33], v[28:29] op_sel_hi:[0,1]
	v_pk_mul_f32 v[20:21], v[16:17], v[20:21]
	v_pk_mul_f32 v[16:17], v[32:33], v[22:23] op_sel_hi:[0,1]
	v_pk_mul_f32 v[22:23], v[18:19], v[16:17]
	v_cvt_pk_bf16_f32 v16, v24, v25
	v_cvt_pk_bf16_f32 v17, v26, v27
	v_cvt_pk_bf16_f32 v18, v20, v21
	s_nop 0
	v_cvt_pk_bf16_f32 v19, v22, v23
	v_add_u32_e32 v23, 0xb0, v142
	v_and_b32_e32 v20, 0xff, v23
	v_lshl_add_u32 v20, v20, 2, s17
	ds_read_b32 v26, v20
	v_mad_i64_i32 v[20:21], s[26:27], v39, s51, v[112:113]
	v_lshl_add_u64 v[20:21], v[20:21], 0, v[114:115]
	global_store_dwordx4 v[20:21], v[16:19], off
	s_waitcnt lgkmcnt(0)
	v_mul_f32_e32 v22, 0xbfb8aa3b, v26
	v_pk_mul_f32 v[24:25], v[8:9], v[22:23] op_sel_hi:[1,0]
	v_pk_mul_f32 v[20:21], v[10:11], v[22:23] op_sel_hi:[1,0]
	v_exp_f32_e32 v24, v24
	v_exp_f32_e32 v25, v25
	v_exp_f32_e32 v20, v20
	v_exp_f32_e32 v21, v21
	v_pk_mul_f32 v[10:11], v[10:11], v[14:15]
	v_pk_add_f32 v[18:19], v[24:25], 1.0 op_sel_hi:[1,0]
	v_mul_f32_e32 v16, v26, v26
	v_rcp_f32_e32 v18, v18
	v_rcp_f32_e32 v19, v19
	v_pk_add_f32 v[14:15], v[20:21], 1.0 op_sel_hi:[1,0]
	v_pk_mul_f32 v[8:9], v[8:9], v[12:13]
	v_rcp_f32_e32 v14, v14
	v_rcp_f32_e32 v15, v15
	v_pk_mul_f32 v[12:13], v[16:17], v[18:19] op_sel_hi:[0,1]
	v_pk_mul_f32 v[18:19], v[0:1], v[22:23] op_sel_hi:[1,0]
	v_pk_mul_f32 v[8:9], v[8:9], v[12:13]
	v_exp_f32_e32 v18, v18
	v_exp_f32_e32 v19, v19
	v_pk_mul_f32 v[12:13], v[16:17], v[14:15] op_sel_hi:[0,1]
	v_pk_mul_f32 v[14:15], v[2:3], v[22:23] op_sel_hi:[1,0]
	v_pk_mul_f32 v[10:11], v[10:11], v[12:13]
	v_exp_f32_e32 v14, v14
	v_exp_f32_e32 v15, v15
	v_pk_add_f32 v[12:13], v[18:19], 1.0 op_sel_hi:[1,0]
	v_pk_mul_f32 v[2:3], v[2:3], v[6:7]
	v_rcp_f32_e32 v12, v12
	v_rcp_f32_e32 v13, v13
	v_pk_add_f32 v[6:7], v[14:15], 1.0 op_sel_hi:[1,0]
	v_pk_mul_f32 v[0:1], v[0:1], v[4:5]
	v_rcp_f32_e32 v6, v6
	v_rcp_f32_e32 v7, v7
	v_pk_mul_f32 v[4:5], v[16:17], v[12:13] op_sel_hi:[0,1]
	v_pk_mul_f32 v[4:5], v[0:1], v[4:5]
	v_pk_mul_f32 v[0:1], v[16:17], v[6:7] op_sel_hi:[0,1]
	v_pk_mul_f32 v[6:7], v[2:3], v[0:1]
	v_cvt_pk_bf16_f32 v0, v8, v9
	v_cvt_pk_bf16_f32 v1, v10, v11
	v_cvt_pk_bf16_f32 v2, v4, v5
	v_mad_i64_i32 v[4:5], s[26:27], v23, s51, v[112:113]
	v_lshl_add_u64 v[4:5], v[4:5], 0, v[114:115]
	s_mov_b64 s[26:27], s[20:21]
	v_cvt_pk_bf16_f32 v3, v6, v7
	global_store_dwordx4 v[4:5], v[0:3], off
	s_cbranch_vccz .LBB0_229
	s_waitcnt vmcnt(0)
	s_cmpk_gt_u32 s38, 0xff
	s_cbranch_scc1 .LBB0_236
	s_barrier

.LBB0_357:
	ds_read_b128 v[134:137], v190
	ds_read_b128 v[138:141], v190 offset:1024
	ds_read_b128 v[142:145], v190 offset:2048
	ds_read_b128 v[146:149], v190 offset:3072
	s_mov_b32 m0, s54
	v_lshl_add_u64 v[150:151], v[128:129], 0, s[34:35]
	ds_read_b128 v[166:169], v191
	ds_read_b128 v[170:173], v191 offset:1024
	ds_read_b128 v[174:177], v191 offset:2048
	ds_read_b128 v[178:181], v191 offset:3072
	ds_read_b128 v[194:197], v191 offset:4096
	ds_read_b128 v[198:201], v191 offset:5120
	ds_read_b128 v[202:205], v191 offset:6144
	ds_read_b128 v[206:209], v191 offset:7168
	global_load_lds_dwordx4 v[150:151], off
	v_lshl_add_u64 v[150:151], v[130:131], 0, s[34:35]
	s_mov_b32 m0, s55
	s_nop 0
	global_load_lds_dwordx4 v[150:151], off
	s_waitcnt lgkmcnt(8)
	s_barrier
	s_waitcnt lgkmcnt(0)
	s_setprio 1
	s_waitcnt lgkmcnt(0)
	v_mfma_f32_16x16x32_bf16 v[116:119], v[134:137], v[166:169], v[116:119]
	s_add_i32 s36, s34, 0xfff50080
	v_mfma_f32_16x16x32_bf16 v[112:115], v[142:145], v[166:169], v[112:115]
	s_cmp_eq_u32 s67, 40
	v_mfma_f32_16x16x32_bf16 v[108:111], v[134:137], v[174:177], v[108:111]
	s_cselect_b32 s69, s27, s29
	v_mfma_f32_16x16x32_bf16 v[104:107], v[142:145], v[174:177], v[104:107]
	s_cselect_b32 s68, s26, s28
	v_mfma_f32_16x16x32_bf16 v[92:95], v[134:137], v[194:197], v[92:95]
	s_cselect_b32 s37, s9, s31
	v_mfma_f32_16x16x32_bf16 v[88:91], v[142:145], v[194:197], v[88:91]
	s_cselect_b32 s70, s8, s30
	v_mfma_f32_16x16x32_bf16 v[76:79], v[134:137], v[202:205], v[76:79]
	v_mfma_f32_16x16x32_bf16 v[72:75], v[142:145], v[202:205], v[72:75]
	v_mfma_f32_16x16x32_bf16 v[116:119], v[138:141], v[170:173], v[116:119]
	v_mfma_f32_16x16x32_bf16 v[112:115], v[146:149], v[170:173], v[112:115]
	v_mfma_f32_16x16x32_bf16 v[108:111], v[138:141], v[178:181], v[108:111]
	v_mfma_f32_16x16x32_bf16 v[104:107], v[146:149], v[178:181], v[104:107]
	v_mfma_f32_16x16x32_bf16 v[92:95], v[138:141], v[198:201], v[92:95]
	v_mfma_f32_16x16x32_bf16 v[88:91], v[146:149], v[198:201], v[88:91]
	v_mfma_f32_16x16x32_bf16 v[76:79], v[138:141], v[206:209], v[76:79]
	v_mfma_f32_16x16x32_bf16 v[72:75], v[146:149], v[206:209], v[72:75]
	s_setprio 0
	s_barrier
	s_cselect_b32 s71, 0, s36
	s_add_u32 s36, s70, s71
	s_addc_u32 s37, s37, 0
	s_mov_b32 m0, s56
	v_lshl_add_u64 v[150:151], s[36:37], 0, v[156:157]
	ds_read_b128 v[210:213], v192
	ds_read_b128 v[214:217], v192 offset:1024
	ds_read_b128 v[222:225], v192 offset:2048
	ds_read_b128 v[226:229], v192 offset:3072
	global_load_lds_dwordx4 v[150:151], off
	v_lshl_add_u64 v[182:183], s[36:37], 0, v[160:161]
	s_mov_b32 m0, s57
	s_nop 0
	global_load_lds_dwordx4 v[182:183], off
	s_barrier
	s_waitcnt lgkmcnt(0)
	s_setprio 1
	s_waitcnt lgkmcnt(0)
	v_mfma_f32_16x16x32_bf16 v[124:127], v[210:213], v[166:169], v[124:127]
	v_mfma_f32_16x16x32_bf16 v[120:123], v[222:225], v[166:169], v[120:123]
	v_mfma_f32_16x16x32_bf16 v[100:103], v[210:213], v[174:177], v[100:103]
	v_mfma_f32_16x16x32_bf16 v[96:99], v[222:225], v[174:177], v[96:99]
	v_mfma_f32_16x16x32_bf16 v[84:87], v[210:213], v[194:197], v[84:87]
	v_mfma_f32_16x16x32_bf16 v[80:83], v[222:225], v[194:197], v[80:83]
	v_mfma_f32_16x16x32_bf16 v[68:71], v[210:213], v[202:205], v[68:71]
	v_mfma_f32_16x16x32_bf16 v[64:67], v[222:225], v[202:205], v[64:67]
	v_mfma_f32_16x16x32_bf16 v[124:127], v[214:217], v[170:173], v[124:127]
	v_mfma_f32_16x16x32_bf16 v[120:123], v[226:229], v[170:173], v[120:123]
	v_mfma_f32_16x16x32_bf16 v[100:103], v[214:217], v[178:181], v[100:103]
	v_mfma_f32_16x16x32_bf16 v[96:99], v[226:229], v[178:181], v[96:99]
	v_mfma_f32_16x16x32_bf16 v[84:87], v[214:217], v[198:201], v[84:87]
	v_mfma_f32_16x16x32_bf16 v[80:83], v[226:229], v[198:201], v[80:83]
	v_mfma_f32_16x16x32_bf16 v[68:71], v[214:217], v[206:209], v[68:71]
	v_mfma_f32_16x16x32_bf16 v[64:67], v[226:229], v[206:209], v[64:67]
	s_setprio 0
	s_add_u32 s68, s68, s71
	s_addc_u32 s69, s69, 0
	s_mov_b32 m0, s46
	v_lshl_add_u64 v[218:219], s[68:69], 0, v[154:155]
	s_barrier
	ds_read_b128 v[166:169], v191 offset:16384
	ds_read_b128 v[170:173], v191 offset:17408
	ds_read_b128 v[174:177], v191 offset:18432
	ds_read_b128 v[178:181], v191 offset:19456
	ds_read_b128 v[194:197], v191 offset:20480
	ds_read_b128 v[198:201], v191 offset:21504
	ds_read_b128 v[202:205], v191 offset:22528
	ds_read_b128 v[206:209], v191 offset:23552
	global_load_lds_dwordx4 v[218:219], off
	v_lshl_add_u64 v[230:231], s[68:69], 0, v[158:159]
	s_mov_b32 m0, s47
	s_nop 0
	global_load_lds_dwordx4 v[230:231], off
	s_barrier
	s_waitcnt lgkmcnt(0)
	s_setprio 1
	s_waitcnt lgkmcnt(0)
	v_mfma_f32_16x16x32_bf16 v[52:55], v[134:137], v[166:169], v[52:55]
	v_mfma_f32_16x16x32_bf16 v[48:51], v[142:145], v[166:169], v[48:51]
	v_mfma_f32_16x16x32_bf16 v[44:47], v[134:137], v[174:177], v[44:47]
	v_mfma_f32_16x16x32_bf16 v[36:39], v[142:145], v[174:177], v[36:39]
	v_mfma_f32_16x16x32_bf16 v[28:31], v[134:137], v[194:197], v[28:31]
	v_mfma_f32_16x16x32_bf16 v[20:23], v[142:145], v[194:197], v[20:23]
	v_mfma_f32_16x16x32_bf16 v[12:15], v[134:137], v[202:205], v[12:15]
	v_mfma_f32_16x16x32_bf16 v[4:7], v[142:145], v[202:205], v[4:7]
	v_mfma_f32_16x16x32_bf16 v[52:55], v[138:141], v[170:173], v[52:55]
	v_mfma_f32_16x16x32_bf16 v[48:51], v[146:149], v[170:173], v[48:51]
	v_mfma_f32_16x16x32_bf16 v[44:47], v[138:141], v[178:181], v[44:47]
	v_mfma_f32_16x16x32_bf16 v[36:39], v[146:149], v[178:181], v[36:39]
	v_mfma_f32_16x16x32_bf16 v[28:31], v[138:141], v[198:201], v[28:31]
	v_mfma_f32_16x16x32_bf16 v[20:23], v[146:149], v[198:201], v[20:23]
	v_mfma_f32_16x16x32_bf16 v[12:15], v[138:141], v[206:209], v[12:15]
	v_mfma_f32_16x16x32_bf16 v[4:7], v[146:149], v[206:209], v[4:7]
	s_setprio 0
	s_barrier
	s_add_u32 s70, s36, 0xb0000
	s_addc_u32 s71, s37, 0
	s_mov_b32 m0, s0
	v_lshl_add_u64 v[134:135], s[70:71], 0, v[156:157]
	global_load_lds_dwordx4 v[134:135], off
	v_lshl_add_u64 v[134:135], s[70:71], 0, v[160:161]
	s_mov_b32 m0, s62
	s_nop 0
	global_load_lds_dwordx4 v[134:135], off
	s_waitcnt vmcnt(6)
	s_barrier
	s_setprio 1
	v_mfma_f32_16x16x32_bf16 v[60:63], v[210:213], v[166:169], v[60:63]
	v_mfma_f32_16x16x32_bf16 v[56:59], v[222:225], v[166:169], v[56:59]
	v_mfma_f32_16x16x32_bf16 v[40:43], v[210:213], v[174:177], v[40:43]
	v_mfma_f32_16x16x32_bf16 v[32:35], v[222:225], v[174:177], v[32:35]
	v_mfma_f32_16x16x32_bf16 v[24:27], v[210:213], v[194:197], v[24:27]
	v_mfma_f32_16x16x32_bf16 v[16:19], v[222:225], v[194:197], v[16:19]
	v_mfma_f32_16x16x32_bf16 v[8:11], v[210:213], v[202:205], v[8:11]
	v_mfma_f32_16x16x32_bf16 v[0:3], v[222:225], v[202:205], v[0:3]
	v_mfma_f32_16x16x32_bf16 v[60:63], v[214:217], v[170:173], v[60:63]
	v_mfma_f32_16x16x32_bf16 v[56:59], v[226:229], v[170:173], v[56:59]
	v_mfma_f32_16x16x32_bf16 v[40:43], v[214:217], v[178:181], v[40:43]
	v_mfma_f32_16x16x32_bf16 v[32:35], v[226:229], v[178:181], v[32:35]
	v_mfma_f32_16x16x32_bf16 v[24:27], v[214:217], v[198:201], v[24:27]
	v_mfma_f32_16x16x32_bf16 v[16:19], v[226:229], v[198:201], v[16:19]
	v_mfma_f32_16x16x32_bf16 v[8:11], v[214:217], v[206:209], v[8:11]
	v_mfma_f32_16x16x32_bf16 v[0:3], v[226:229], v[206:209], v[0:3]
	s_setprio 0
	s_barrier
	ds_read_b128 v[134:137], v132
	ds_read_b128 v[138:141], v132 offset:1024
	ds_read_b128 v[142:145], v132 offset:2048
	ds_read_b128 v[146:149], v132 offset:3072
	s_add_u32 s68, s68, 0xb0000
	s_addc_u32 s69, s69, 0
	s_mov_b32 m0, s48
	v_lshl_add_u64 v[210:211], s[68:69], 0, v[154:155]
	ds_read_b128 v[166:169], v191 offset:32768
	ds_read_b128 v[170:173], v191 offset:33792
	ds_read_b128 v[174:177], v191 offset:34816
	ds_read_b128 v[178:181], v191 offset:35840
	ds_read_b128 v[194:197], v191 offset:36864
	ds_read_b128 v[198:201], v191 offset:37888
	ds_read_b128 v[202:205], v191 offset:38912
	ds_read_b128 v[206:209], v191 offset:39936
	global_load_lds_dwordx4 v[210:211], off
	v_lshl_add_u64 v[210:211], s[68:69], 0, v[158:159]
	s_mov_b32 m0, s49
	s_nop 0
	global_load_lds_dwordx4 v[210:211], off
	s_waitcnt lgkmcnt(8)
	s_barrier
	s_waitcnt lgkmcnt(0)
	s_setprio 1
	s_waitcnt lgkmcnt(0)
	v_mfma_f32_16x16x32_bf16 v[116:119], v[134:137], v[166:169], v[116:119]
	v_mfma_f32_16x16x32_bf16 v[112:115], v[142:145], v[166:169], v[112:115]
	v_mfma_f32_16x16x32_bf16 v[108:111], v[134:137], v[174:177], v[108:111]
	v_mfma_f32_16x16x32_bf16 v[104:107], v[142:145], v[174:177], v[104:107]
	v_mfma_f32_16x16x32_bf16 v[92:95], v[134:137], v[194:197], v[92:95]
	v_mfma_f32_16x16x32_bf16 v[88:91], v[142:145], v[194:197], v[88:91]
	v_mfma_f32_16x16x32_bf16 v[76:79], v[134:137], v[202:205], v[76:79]
	v_mfma_f32_16x16x32_bf16 v[72:75], v[142:145], v[202:205], v[72:75]
	v_mfma_f32_16x16x32_bf16 v[116:119], v[138:141], v[170:173], v[116:119]
	v_mfma_f32_16x16x32_bf16 v[112:115], v[146:149], v[170:173], v[112:115]
	v_mfma_f32_16x16x32_bf16 v[108:111], v[138:141], v[178:181], v[108:111]
	v_mfma_f32_16x16x32_bf16 v[104:107], v[146:149], v[178:181], v[104:107]
	v_mfma_f32_16x16x32_bf16 v[92:95], v[138:141], v[198:201], v[92:95]
	v_mfma_f32_16x16x32_bf16 v[88:91], v[146:149], v[198:201], v[88:91]
	v_mfma_f32_16x16x32_bf16 v[76:79], v[138:141], v[206:209], v[76:79]
	v_mfma_f32_16x16x32_bf16 v[72:75], v[146:149], v[206:209], v[72:75]
	s_setprio 0
	s_barrier
	s_mov_b32 m0, s63
	v_lshl_add_u64 v[150:151], v[150:151], 0, s[10:11]
	ds_read_b128 v[210:213], v133
	ds_read_b128 v[214:217], v133 offset:1024
	ds_read_b128 v[222:225], v133 offset:2048
	ds_read_b128 v[226:229], v133 offset:3072
	global_load_lds_dwordx4 v[150:151], off
	v_lshl_add_u64 v[150:151], v[182:183], 0, s[10:11]
	s_mov_b32 m0, s64
	s_nop 0
	global_load_lds_dwordx4 v[150:151], off
	s_barrier
	s_waitcnt lgkmcnt(0)
	s_setprio 1
	s_waitcnt lgkmcnt(0)
	v_mfma_f32_16x16x32_bf16 v[124:127], v[210:213], v[166:169], v[124:127]
	v_mfma_f32_16x16x32_bf16 v[120:123], v[222:225], v[166:169], v[120:123]
	v_mfma_f32_16x16x32_bf16 v[100:103], v[210:213], v[174:177], v[100:103]
	v_mfma_f32_16x16x32_bf16 v[96:99], v[222:225], v[174:177], v[96:99]
	v_mfma_f32_16x16x32_bf16 v[84:87], v[210:213], v[194:197], v[84:87]
	v_mfma_f32_16x16x32_bf16 v[80:83], v[222:225], v[194:197], v[80:83]
	v_mfma_f32_16x16x32_bf16 v[68:71], v[210:213], v[202:205], v[68:71]
	v_mfma_f32_16x16x32_bf16 v[64:67], v[222:225], v[202:205], v[64:67]
	v_mfma_f32_16x16x32_bf16 v[124:127], v[214:217], v[170:173], v[124:127]
	v_mfma_f32_16x16x32_bf16 v[120:123], v[226:229], v[170:173], v[120:123]
	v_mfma_f32_16x16x32_bf16 v[100:103], v[214:217], v[178:181], v[100:103]
	v_mfma_f32_16x16x32_bf16 v[96:99], v[226:229], v[178:181], v[96:99]
	v_mfma_f32_16x16x32_bf16 v[84:87], v[214:217], v[198:201], v[84:87]
	v_mfma_f32_16x16x32_bf16 v[80:83], v[226:229], v[198:201], v[80:83]
	v_mfma_f32_16x16x32_bf16 v[68:71], v[214:217], v[206:209], v[68:71]
	v_mfma_f32_16x16x32_bf16 v[64:67], v[226:229], v[206:209], v[64:67]
	s_setprio 0
	s_mov_b32 m0, s51
	v_lshl_add_u64 v[150:151], v[218:219], 0, s[10:11]
	s_barrier
	ds_read_b128 v[166:169], v191 offset:49152
	ds_read_b128 v[170:173], v191 offset:50176
	ds_read_b128 v[174:177], v191 offset:51200
	ds_read_b128 v[178:181], v191 offset:52224
	ds_read_b128 v[194:197], v191 offset:53248
	ds_read_b128 v[198:201], v191 offset:54272
	ds_read_b128 v[202:205], v191 offset:55296
	ds_read_b128 v[206:209], v191 offset:56320
	global_load_lds_dwordx4 v[150:151], off
	v_lshl_add_u64 v[150:151], v[230:231], 0, s[10:11]
	s_mov_b32 m0, s52
	s_nop 0
	global_load_lds_dwordx4 v[150:151], off
	s_barrier
;     ...
;         G_PAIR(0, 1);
; #pragma unroll 1
;         for (int t = 2; t < nt; t += 2) G_PAIR(t, 0);
	s_waitcnt lgkmcnt(0)
	s_setprio 1
	s_waitcnt lgkmcnt(0)
	v_mfma_f32_16x16x32_bf16 v[52:55], v[134:137], v[166:169], v[52:55]
	v_mfma_f32_16x16x32_bf16 v[48:51], v[142:145], v[166:169], v[48:51]
	v_mfma_f32_16x16x32_bf16 v[44:47], v[134:137], v[174:177], v[44:47]
	v_mfma_f32_16x16x32_bf16 v[36:39], v[142:145], v[174:177], v[36:39]
	v_mfma_f32_16x16x32_bf16 v[28:31], v[134:137], v[194:197], v[28:31]
	v_mfma_f32_16x16x32_bf16 v[20:23], v[142:145], v[194:197], v[20:23]
	v_mfma_f32_16x16x32_bf16 v[12:15], v[134:137], v[202:205], v[12:15]
	v_mfma_f32_16x16x32_bf16 v[4:7], v[142:145], v[202:205], v[4:7]
	v_mfma_f32_16x16x32_bf16 v[52:55], v[138:141], v[170:173], v[52:55]
	v_mfma_f32_16x16x32_bf16 v[48:51], v[146:149], v[170:173], v[48:51]
	v_mfma_f32_16x16x32_bf16 v[44:47], v[138:141], v[178:181], v[44:47]
	v_mfma_f32_16x16x32_bf16 v[36:39], v[146:149], v[178:181], v[36:39]
	v_mfma_f32_16x16x32_bf16 v[28:31], v[138:141], v[198:201], v[28:31]
	v_mfma_f32_16x16x32_bf16 v[20:23], v[146:149], v[198:201], v[20:23]
	v_mfma_f32_16x16x32_bf16 v[12:15], v[138:141], v[206:209], v[12:15]
	v_mfma_f32_16x16x32_bf16 v[4:7], v[146:149], v[206:209], v[4:7]
	s_setprio 0
	s_barrier
	s_add_u32 s36, s36, 0xb0080
	s_addc_u32 s37, s37, 0
	s_mov_b32 m0, s65
	v_lshl_add_u64 v[134:135], s[36:37], 0, v[156:157]
	global_load_lds_dwordx4 v[134:135], off
	v_lshl_add_u64 v[134:135], s[36:37], 0, v[160:161]
	s_mov_b32 m0, s66
	s_nop 0
	global_load_lds_dwordx4 v[134:135], off
	s_waitcnt vmcnt(6)
	s_barrier
	s_setprio 1
	v_mfma_f32_16x16x32_bf16 v[60:63], v[210:213], v[166:169], v[60:63]
	v_mfma_f32_16x16x32_bf16 v[56:59], v[222:225], v[166:169], v[56:59]
	v_mfma_f32_16x16x32_bf16 v[40:43], v[210:213], v[174:177], v[40:43]
	v_mfma_f32_16x16x32_bf16 v[32:35], v[222:225], v[174:177], v[32:35]
	v_mfma_f32_16x16x32_bf16 v[24:27], v[210:213], v[194:197], v[24:27]
	v_mfma_f32_16x16x32_bf16 v[16:19], v[222:225], v[194:197], v[16:19]
	v_mfma_f32_16x16x32_bf16 v[8:11], v[210:213], v[202:205], v[8:11]
	v_mfma_f32_16x16x32_bf16 v[0:3], v[222:225], v[202:205], v[0:3]
	v_mfma_f32_16x16x32_bf16 v[60:63], v[214:217], v[170:173], v[60:63]
	v_mfma_f32_16x16x32_bf16 v[56:59], v[226:229], v[170:173], v[56:59]
	v_mfma_f32_16x16x32_bf16 v[40:43], v[214:217], v[178:181], v[40:43]
	v_mfma_f32_16x16x32_bf16 v[32:35], v[226:229], v[178:181], v[32:35]
	v_mfma_f32_16x16x32_bf16 v[24:27], v[214:217], v[198:201], v[24:27]
	v_mfma_f32_16x16x32_bf16 v[16:19], v[226:229], v[198:201], v[16:19]
	v_mfma_f32_16x16x32_bf16 v[8:11], v[214:217], v[206:209], v[8:11]
	v_mfma_f32_16x16x32_bf16 v[0:3], v[226:229], v[206:209], v[0:3]
	s_setprio 0
	s_add_i32 s67, s67, 2
	s_add_u32 s34, s34, 0x100
	s_addc_u32 s35, s35, 0
	s_cmp_gt_u32 s67, 41
	s_barrier
	s_cbranch_scc0 .LBB0_357
; __device__ __forceinline__ unsigned pk2(float lo, float hi) { unsigned r; asm volatile("v_cvt_pk_bf16_f32 %0, %1, %2" : "=v"(r) : "v"(lo), "v"(hi)); return r; }
; __device__ __forceinline__ unsigned pk2(float lo, float hi) { return f2bf(lo) | (f2bf(hi) << 16); }
;     __device__ __forceinline__ void epi(const f32x4 (&acc)[2][2][4][2], const Unit& u, int wr, int wc, int fr, int fq) const {
;     ...
;         const int row0 = u.pm * 256 + wr * 64 + fr, col0 = u.pn * 256 + wc * 32 + 8 * fq;
; #pragma unroll
;         for (int ai = 0; ai < 2; ++ai) {
;             u32x4 xo[4][2];
; #pragma unroll
;             for (int m = 0; m < 4; ++m)
; #pragma unroll
;                 for (int bj = 0; bj < 2; ++bj) xo[m][bj] = *(const u32x4*)(xb + (size_t)(row0 + ai * 128 + m * 16) * D + col0 + bj * 128);
; #pragma unroll
;             for (int m = 0; m < 4; ++m) {
;                 const int row = row0 + ai * 128 + m * 16; const size_t off = (size_t)row * D + col0; float ss = 0.f;
; #pragma unroll
;                 for (int bj = 0; bj < 2; ++bj) {
;                     const u32x4 o = xo[m][bj]; const f32x4 a0v = acc[ai][bj][m][0], a1v = acc[ai][bj][m][1];
;                     const float v0 = bf_lo(o.x) + coef * a0v[0], v1 = bf_hi(o.x) + coef * a0v[1], v2 = bf_lo(o.y) + coef * a0v[2], v3 = bf_hi(o.y) + coef * a0v[3];
;                     const float v4 = bf_lo(o.z) + coef * a1v[0], v5 = bf_hi(o.z) + coef * a1v[1], v6 = bf_lo(o.w) + coef * a1v[2], v7 = bf_hi(o.w) + coef * a1v[3];
;                     u32x4 w; w.x = pk2(v0, v1); w.y = pk2(v2, v3); w.z = pk2(v4, v5); w.w = pk2(v6, v7);
;                     *(u32x4*)(xb + off + bj * 128) = w;
;                     ss += ((v0 * v0 + v1 * v1) + (v2 * v2 + v3 * v3)) + ((v4 * v4 + v5 * v5) + (v6 * v6 + v7 * v7));
;                 }
;                 ss += __shfl_xor(ss, 16); ss += __shfl_xor(ss, 32);
;                 if (fq == 0) rowss[(size_t)row * 32 + u.pn * 4 + wc] = ss;
	v_lshl_or_b32 v166, s40, 8, v189
	v_lshl_add_u32 v170, s61, 8, v153
	v_ashrrev_i32_e32 v167, 31, v166
	v_lshlrev_b64 v[202:203], 1, v[166:167]
	v_ashrrev_i32_e32 v171, 31, v170
	v_lshl_add_u64 v[168:169], s[20:21], 0, v[202:203]
	v_lshlrev_b64 v[204:205], 11, v[170:171]
	v_lshl_add_u64 v[128:129], v[168:169], 0, v[204:205]
	global_load_dwordx4 v[194:197], v[128:129], off
	global_load_dwordx4 v[198:201], v[128:129], off offset:256
	v_or_b32_e32 v180, 16, v170
	v_or_b32_e32 v176, 32, v170
	v_or_b32_e32 v172, 48, v170
	v_ashrrev_i32_e32 v181, 31, v180
	v_ashrrev_i32_e32 v177, 31, v176
	v_ashrrev_i32_e32 v173, 31, v172
	v_lshlrev_b64 v[182:183], 11, v[180:181]
	v_lshlrev_b64 v[178:179], 11, v[176:177]
	v_lshlrev_b64 v[174:175], 11, v[172:173]
	v_lshl_add_u64 v[128:129], v[168:169], 0, v[182:183]
	v_lshl_add_u64 v[130:131], v[168:169], 0, v[178:179]
	v_lshl_add_u64 v[206:207], v[168:169], 0, v[174:175]
	global_load_dwordx4 v[148:151], v[128:129], off
	global_load_dwordx4 v[144:147], v[128:129], off offset:256
	global_load_dwordx4 v[140:143], v[130:131], off
	global_load_dwordx4 v[136:139], v[130:131], off offset:256
	global_load_dwordx4 v[132:135], v[206:207], off
	s_nop 0
	global_load_dwordx4 v[128:131], v[206:207], off offset:256
	v_and_b32_e32 v206, 64, v193
	v_xor_b32_e32 v208, 16, v193
	v_add_u32_e32 v206, 64, v206
	v_cmp_lt_i32_e32 vcc, v208, v206
	s_waitcnt vmcnt(0)
	v_lshlrev_b32_e32 v209, 16, v195
	v_cndmask_b32_e32 v207, v193, v208, vcc
	v_lshlrev_b32_e32 v208, 16, v194
	v_and_b32_e32 v194, 0xffff0000, v194
	v_and_b32_e32 v195, 0xffff0000, v195
	v_lshlrev_b32_e32 v210, 16, v196
	v_and_b32_e32 v196, 0xffff0000, v196
	v_lshlrev_b32_e32 v211, 16, v197
	v_and_b32_e32 v197, 0xffff0000, v197
	v_lshlrev_b32_e32 v212, 16, v198
	v_and_b32_e32 v198, 0xffff0000, v198
	v_lshlrev_b32_e32 v213, 16, v199
	v_and_b32_e32 v199, 0xffff0000, v199
	v_lshlrev_b32_e32 v214, 16, v200
	v_and_b32_e32 v200, 0xffff0000, v200
	v_lshlrev_b32_e32 v215, 16, v201
	v_and_b32_e32 v201, 0xffff0000, v201
	v_fmac_f32_e32 v194, 0.5, v117
	v_fmac_f32_e32 v195, 0.5, v119
	v_fmac_f32_e32 v196, 0.5, v113
	v_fmac_f32_e32 v197, 0.5, v115
	v_fmac_f32_e32 v198, 0.5, v125
	v_fmac_f32_e32 v199, 0.5, v127
	v_fmac_f32_e32 v200, 0.5, v121
	v_fmac_f32_e32 v201, 0.5, v123
	v_fmac_f32_e32 v208, 0.5, v116
	v_fmac_f32_e32 v209, 0.5, v118
	v_fmac_f32_e32 v210, 0.5, v112
	v_fmac_f32_e32 v211, 0.5, v114
	v_fmac_f32_e32 v212, 0.5, v124
	v_fmac_f32_e32 v213, 0.5, v126
	v_fmac_f32_e32 v214, 0.5, v120
	v_fmac_f32_e32 v215, 0.5, v122
	v_mul_f32_e32 v112, v194, v194
	v_mul_f32_e32 v113, v195, v195
	v_mul_f32_e32 v118, v196, v196
	v_mul_f32_e32 v119, v197, v197
	v_mul_f32_e32 v120, v198, v198
	v_mul_f32_e32 v121, v199, v199
	v_mul_f32_e32 v122, v200, v200
	v_mul_f32_e32 v123, v201, v201
	v_fmac_f32_e32 v112, v208, v208
	v_fmac_f32_e32 v113, v209, v209
	v_fmac_f32_e32 v118, v210, v210
	v_fmac_f32_e32 v119, v211, v211
	v_fmac_f32_e32 v120, v212, v212
	v_fmac_f32_e32 v121, v213, v213
	v_fmac_f32_e32 v122, v214, v214
	v_fmac_f32_e32 v123, v215, v215
	v_add_f32_e32 v112, v112, v113
	v_add_f32_e32 v113, v118, v119
	v_add_f32_e32 v118, v120, v121
	v_add_f32_e32 v119, v122, v123
	v_add_f32_e32 v112, v112, v113
	v_add_f32_e32 v113, v118, v119
	v_add_f32_e32 v113, v112, v113
	v_lshlrev_b32_e32 v112, 2, v207
	ds_bpermute_b32 v122, v112, v113
	v_lshl_add_u64 v[118:119], s[20:21], 0, v[204:205]
	v_cvt_pk_bf16_f32 v114, v208, v194
	v_lshl_add_u64 v[120:121], v[118:119], 0, v[202:203]
	v_cvt_pk_bf16_f32 v115, v209, v195
	v_cvt_pk_bf16_f32 v116, v210, v196
	v_cvt_pk_bf16_f32 v117, v211, v197
	global_store_dwordx4 v[120:121], v[114:117], off
	s_waitcnt lgkmcnt(0)
	s_nop 0
	v_add_f32_e32 v114, v113, v122
	v_xor_b32_e32 v113, 32, v193
	v_cmp_lt_i32_e32 vcc, v113, v206
	v_cvt_pk_bf16_f32 v116, v212, v198
	v_cvt_pk_bf16_f32 v117, v213, v199
	v_cvt_pk_bf16_f32 v118, v214, v200
	v_cvt_pk_bf16_f32 v119, v215, v201
	global_store_dwordx4 v[120:121], v[116:119], off offset:256
	s_nop 0
	v_cndmask_b32_e32 v113, v193, v113, vcc
	v_lshlrev_b32_e32 v113, 2, v113
	ds_bpermute_b32 v115, v113, v114
	s_and_saveexec_b64 s[28:29], s[6:7]
	s_cbranch_execz .LBB0_360
	s_waitcnt lgkmcnt(0)
	v_add_f32_e32 v116, v114, v115
	s_lshl_b32 s30, s40, 2
	v_lshlrev_b64 v[114:115], 7, v[170:171]
	s_ashr_i32 s31, s30, 31
	v_lshl_add_u64 v[114:115], s[2:3], 0, v[114:115]
	v_lshl_add_u64 v[114:115], s[30:31], 2, v[114:115]
	s_lshl_b32 s0, s50, 2
	v_lshl_add_u64 v[114:115], v[114:115], 0, s[0:1]
	global_store_dword v[114:115], v116, off

.LBB0_580:
	ds_read_b128 v[150:153], v144
	ds_read_b128 v[154:157], v144 offset:1024
	ds_read_b128 v[158:161], v144 offset:2048
	ds_read_b128 v[162:165], v144 offset:3072
	s_mov_b32 m0, s1
	v_lshl_add_u64 v[198:199], v[138:139], 0, s[44:45]
	ds_read_b128 v[166:169], v145
	ds_read_b128 v[170:173], v145 offset:1024
	ds_read_b128 v[174:177], v145 offset:2048
	ds_read_b128 v[178:181], v145 offset:3072
	ds_read_b128 v[182:185], v145 offset:4096
	ds_read_b128 v[186:189], v145 offset:5120
	ds_read_b128 v[190:193], v145 offset:6144
	ds_read_b128 v[194:197], v145 offset:7168
	global_load_lds_dwordx4 v[198:199], off
	v_lshl_add_u64 v[198:199], v[140:141], 0, s[44:45]
	s_mov_b32 m0, s12
	s_nop 0
	global_load_lds_dwordx4 v[198:199], off
	s_waitcnt lgkmcnt(8)
	s_barrier
	s_waitcnt lgkmcnt(0)
	s_setprio 1
	s_waitcnt lgkmcnt(0)
	v_mfma_f32_16x16x32_bf16 v[28:31], v[150:153], v[166:169], v[28:31]
	s_add_i32 s81, s44, 0xfffc0080
	v_mfma_f32_16x16x32_bf16 v[24:27], v[158:161], v[166:169], v[24:27]
	s_cmp_eq_u32 s80, 4
	v_mfma_f32_16x16x32_bf16 v[20:23], v[150:153], v[174:177], v[20:23]
	s_cselect_b64 s[46:47], -1, 0
	v_mfma_f32_16x16x32_bf16 v[16:19], v[158:161], v[174:177], v[16:19]
	s_and_b64 s[82:83], s[46:47], exec
	v_mfma_f32_16x16x32_bf16 v[12:15], v[150:153], v[182:185], v[12:15]
	s_cselect_b32 s83, s39, s5
	v_mfma_f32_16x16x32_bf16 v[8:11], v[158:161], v[182:185], v[8:11]
	s_cselect_b32 s82, s38, s4
	v_mfma_f32_16x16x32_bf16 v[4:7], v[150:153], v[190:193], v[4:7]
	s_cselect_b32 s81, 0, s81
	v_mfma_f32_16x16x32_bf16 v[0:3], v[158:161], v[190:193], v[0:3]
	s_and_b64 s[46:47], s[42:43], s[46:47]
	v_mfma_f32_16x16x32_bf16 v[28:31], v[154:157], v[170:173], v[28:31]
	s_and_b64 s[46:47], s[46:47], exec
	v_mfma_f32_16x16x32_bf16 v[24:27], v[162:165], v[170:173], v[24:27]
	s_cselect_b32 s47, s41, s7
	v_mfma_f32_16x16x32_bf16 v[20:23], v[154:157], v[178:181], v[20:23]
	s_cselect_b32 s46, s40, s6
	v_mfma_f32_16x16x32_bf16 v[16:19], v[162:165], v[178:181], v[16:19]
	v_mfma_f32_16x16x32_bf16 v[12:15], v[154:157], v[186:189], v[12:15]
	v_mfma_f32_16x16x32_bf16 v[8:11], v[162:165], v[186:189], v[8:11]
	v_mfma_f32_16x16x32_bf16 v[4:7], v[154:157], v[194:197], v[4:7]
	v_mfma_f32_16x16x32_bf16 v[0:3], v[162:165], v[194:197], v[0:3]
	s_setprio 0
	s_barrier
	s_add_u32 s46, s46, s81
	s_addc_u32 s47, s47, 0
	s_mov_b32 m0, s35
	v_lshl_add_u64 v[214:215], s[46:47], 0, v[130:131]
	ds_read_b128 v[198:201], v146
	ds_read_b128 v[202:205], v146 offset:1024
	ds_read_b128 v[206:209], v146 offset:2048
	ds_read_b128 v[210:213], v146 offset:3072
	global_load_lds_dwordx4 v[214:215], off
	v_lshl_add_u64 v[216:217], s[46:47], 0, v[128:129]
	s_mov_b32 m0, s73
	s_nop 0
	global_load_lds_dwordx4 v[216:217], off
	s_barrier
	s_waitcnt lgkmcnt(0)
	s_setprio 1
	s_waitcnt lgkmcnt(0)
	v_mfma_f32_16x16x32_bf16 v[92:95], v[198:201], v[166:169], v[92:95]
	v_mfma_f32_16x16x32_bf16 v[88:91], v[206:209], v[166:169], v[88:91]
	v_mfma_f32_16x16x32_bf16 v[76:79], v[198:201], v[174:177], v[76:79]
	v_mfma_f32_16x16x32_bf16 v[72:75], v[206:209], v[174:177], v[72:75]
	v_mfma_f32_16x16x32_bf16 v[60:63], v[198:201], v[182:185], v[60:63]
	v_mfma_f32_16x16x32_bf16 v[56:59], v[206:209], v[182:185], v[56:59]
	v_mfma_f32_16x16x32_bf16 v[44:47], v[198:201], v[190:193], v[44:47]
	v_mfma_f32_16x16x32_bf16 v[40:43], v[206:209], v[190:193], v[40:43]
	v_mfma_f32_16x16x32_bf16 v[92:95], v[202:205], v[170:173], v[92:95]
	v_mfma_f32_16x16x32_bf16 v[88:91], v[210:213], v[170:173], v[88:91]
	v_mfma_f32_16x16x32_bf16 v[76:79], v[202:205], v[178:181], v[76:79]
	v_mfma_f32_16x16x32_bf16 v[72:75], v[210:213], v[178:181], v[72:75]
	v_mfma_f32_16x16x32_bf16 v[60:63], v[202:205], v[186:189], v[60:63]
	v_mfma_f32_16x16x32_bf16 v[56:59], v[210:213], v[186:189], v[56:59]
	v_mfma_f32_16x16x32_bf16 v[44:47], v[202:205], v[194:197], v[44:47]
	v_mfma_f32_16x16x32_bf16 v[40:43], v[210:213], v[194:197], v[40:43]
	s_setprio 0
	s_add_u32 s82, s82, s81
	s_addc_u32 s83, s83, 0
	s_mov_b32 m0, s52
	v_lshl_add_u64 v[218:219], s[82:83], 0, v[130:131]
	s_barrier
	ds_read_b128 v[166:169], v145 offset:16384
	ds_read_b128 v[170:173], v145 offset:17408
	ds_read_b128 v[174:177], v145 offset:18432
	ds_read_b128 v[178:181], v145 offset:19456
	ds_read_b128 v[182:185], v145 offset:20480
	ds_read_b128 v[186:189], v145 offset:21504
	ds_read_b128 v[190:193], v145 offset:22528
	ds_read_b128 v[194:197], v145 offset:23552
	global_load_lds_dwordx4 v[218:219], off
	v_lshl_add_u64 v[222:223], s[82:83], 0, v[128:129]
	s_mov_b32 m0, s55
	s_nop 0
	global_load_lds_dwordx4 v[222:223], off
	s_barrier
	s_waitcnt lgkmcnt(0)
	s_setprio 1
	s_waitcnt lgkmcnt(0)
	v_mfma_f32_16x16x32_bf16 v[84:87], v[150:153], v[166:169], v[84:87]
	v_mfma_f32_16x16x32_bf16 v[80:83], v[158:161], v[166:169], v[80:83]
	v_mfma_f32_16x16x32_bf16 v[68:71], v[150:153], v[174:177], v[68:71]
	v_mfma_f32_16x16x32_bf16 v[64:67], v[158:161], v[174:177], v[64:67]
	v_mfma_f32_16x16x32_bf16 v[52:55], v[150:153], v[182:185], v[52:55]
	v_mfma_f32_16x16x32_bf16 v[48:51], v[158:161], v[182:185], v[48:51]
	v_mfma_f32_16x16x32_bf16 v[36:39], v[150:153], v[190:193], v[36:39]
	v_mfma_f32_16x16x32_bf16 v[32:35], v[158:161], v[190:193], v[32:35]
	v_mfma_f32_16x16x32_bf16 v[84:87], v[154:157], v[170:173], v[84:87]
	v_mfma_f32_16x16x32_bf16 v[80:83], v[162:165], v[170:173], v[80:83]
	v_mfma_f32_16x16x32_bf16 v[68:71], v[154:157], v[178:181], v[68:71]
	v_mfma_f32_16x16x32_bf16 v[64:67], v[162:165], v[178:181], v[64:67]
	v_mfma_f32_16x16x32_bf16 v[52:55], v[154:157], v[186:189], v[52:55]
	v_mfma_f32_16x16x32_bf16 v[48:51], v[162:165], v[186:189], v[48:51]
	v_mfma_f32_16x16x32_bf16 v[36:39], v[154:157], v[194:197], v[36:39]
	v_mfma_f32_16x16x32_bf16 v[32:35], v[162:165], v[194:197], v[32:35]
	s_setprio 0
	s_barrier
	s_add_u32 s84, s46, 0x40000
	s_addc_u32 s85, s47, 0
	s_mov_b32 m0, s74
	v_lshl_add_u64 v[150:151], s[84:85], 0, v[130:131]
	global_load_lds_dwordx4 v[150:151], off
	v_lshl_add_u64 v[150:151], s[84:85], 0, v[128:129]
	s_mov_b32 m0, s75
	s_nop 0
	global_load_lds_dwordx4 v[150:151], off
	s_waitcnt vmcnt(6)
	s_barrier
	s_setprio 1
	v_mfma_f32_16x16x32_bf16 v[124:127], v[198:201], v[166:169], v[124:127]
	v_mfma_f32_16x16x32_bf16 v[120:123], v[206:209], v[166:169], v[120:123]
	v_mfma_f32_16x16x32_bf16 v[116:119], v[198:201], v[174:177], v[116:119]
	v_mfma_f32_16x16x32_bf16 v[112:115], v[206:209], v[174:177], v[112:115]
	v_mfma_f32_16x16x32_bf16 v[108:111], v[198:201], v[182:185], v[108:111]
	v_mfma_f32_16x16x32_bf16 v[104:107], v[206:209], v[182:185], v[104:107]
	v_mfma_f32_16x16x32_bf16 v[100:103], v[198:201], v[190:193], v[100:103]
	v_mfma_f32_16x16x32_bf16 v[96:99], v[206:209], v[190:193], v[96:99]
	v_mfma_f32_16x16x32_bf16 v[124:127], v[202:205], v[170:173], v[124:127]
	v_mfma_f32_16x16x32_bf16 v[120:123], v[210:213], v[170:173], v[120:123]
	v_mfma_f32_16x16x32_bf16 v[116:119], v[202:205], v[178:181], v[116:119]
	v_mfma_f32_16x16x32_bf16 v[112:115], v[210:213], v[178:181], v[112:115]
	v_mfma_f32_16x16x32_bf16 v[108:111], v[202:205], v[186:189], v[108:111]
	v_mfma_f32_16x16x32_bf16 v[104:107], v[210:213], v[186:189], v[104:107]
	v_mfma_f32_16x16x32_bf16 v[100:103], v[202:205], v[194:197], v[100:103]
	v_mfma_f32_16x16x32_bf16 v[96:99], v[210:213], v[194:197], v[96:99]
	s_setprio 0
	s_barrier
	ds_read_b128 v[150:153], v147
	ds_read_b128 v[154:157], v147 offset:1024
	ds_read_b128 v[158:161], v147 offset:2048
	ds_read_b128 v[162:165], v147 offset:3072
	s_add_u32 s82, s82, 0x40000
	s_addc_u32 s83, s83, 0
	s_mov_b32 m0, s56
	v_lshl_add_u64 v[198:199], s[82:83], 0, v[130:131]
	ds_read_b128 v[166:169], v145 offset:32768
	ds_read_b128 v[170:173], v145 offset:33792
	ds_read_b128 v[174:177], v145 offset:34816
	ds_read_b128 v[178:181], v145 offset:35840
	ds_read_b128 v[182:185], v145 offset:36864
	ds_read_b128 v[186:189], v145 offset:37888
	ds_read_b128 v[190:193], v145 offset:38912
	ds_read_b128 v[194:197], v145 offset:39936
	global_load_lds_dwordx4 v[198:199], off
	v_lshl_add_u64 v[198:199], s[82:83], 0, v[128:129]
	s_mov_b32 m0, s57
	s_nop 0
	global_load_lds_dwordx4 v[198:199], off
	s_waitcnt lgkmcnt(8)
	s_barrier
	s_waitcnt lgkmcnt(0)
	s_setprio 1
	s_waitcnt lgkmcnt(0)
	v_mfma_f32_16x16x32_bf16 v[28:31], v[150:153], v[166:169], v[28:31]
	v_mfma_f32_16x16x32_bf16 v[24:27], v[158:161], v[166:169], v[24:27]
	v_mfma_f32_16x16x32_bf16 v[20:23], v[150:153], v[174:177], v[20:23]
	v_mfma_f32_16x16x32_bf16 v[16:19], v[158:161], v[174:177], v[16:19]
	v_mfma_f32_16x16x32_bf16 v[12:15], v[150:153], v[182:185], v[12:15]
	v_mfma_f32_16x16x32_bf16 v[8:11], v[158:161], v[182:185], v[8:11]
	v_mfma_f32_16x16x32_bf16 v[4:7], v[150:153], v[190:193], v[4:7]
	v_mfma_f32_16x16x32_bf16 v[0:3], v[158:161], v[190:193], v[0:3]
	v_mfma_f32_16x16x32_bf16 v[28:31], v[154:157], v[170:173], v[28:31]
	v_mfma_f32_16x16x32_bf16 v[24:27], v[162:165], v[170:173], v[24:27]
	v_mfma_f32_16x16x32_bf16 v[20:23], v[154:157], v[178:181], v[20:23]
	v_mfma_f32_16x16x32_bf16 v[16:19], v[162:165], v[178:181], v[16:19]
	v_mfma_f32_16x16x32_bf16 v[12:15], v[154:157], v[186:189], v[12:15]
	v_mfma_f32_16x16x32_bf16 v[8:11], v[162:165], v[186:189], v[8:11]
	v_mfma_f32_16x16x32_bf16 v[4:7], v[154:157], v[194:197], v[4:7]
	v_mfma_f32_16x16x32_bf16 v[0:3], v[162:165], v[194:197], v[0:3]
	s_setprio 0
	s_barrier
	s_mov_b32 m0, s76
	v_lshl_add_u64 v[214:215], v[214:215], 0, s[2:3]
	ds_read_b128 v[198:201], v148
	ds_read_b128 v[202:205], v148 offset:1024
	ds_read_b128 v[206:209], v148 offset:2048
	ds_read_b128 v[210:213], v148 offset:3072
	global_load_lds_dwordx4 v[214:215], off
	v_lshl_add_u64 v[214:215], v[216:217], 0, s[2:3]
	s_mov_b32 m0, s77
	s_nop 0
	global_load_lds_dwordx4 v[214:215], off
	s_barrier
	s_waitcnt lgkmcnt(0)
	s_setprio 1
	s_waitcnt lgkmcnt(0)
	v_mfma_f32_16x16x32_bf16 v[92:95], v[198:201], v[166:169], v[92:95]
	v_mfma_f32_16x16x32_bf16 v[88:91], v[206:209], v[166:169], v[88:91]
	v_mfma_f32_16x16x32_bf16 v[76:79], v[198:201], v[174:177], v[76:79]
	v_mfma_f32_16x16x32_bf16 v[72:75], v[206:209], v[174:177], v[72:75]
	v_mfma_f32_16x16x32_bf16 v[60:63], v[198:201], v[182:185], v[60:63]
	v_mfma_f32_16x16x32_bf16 v[56:59], v[206:209], v[182:185], v[56:59]
	v_mfma_f32_16x16x32_bf16 v[44:47], v[198:201], v[190:193], v[44:47]
	v_mfma_f32_16x16x32_bf16 v[40:43], v[206:209], v[190:193], v[40:43]
	v_mfma_f32_16x16x32_bf16 v[92:95], v[202:205], v[170:173], v[92:95]
	v_mfma_f32_16x16x32_bf16 v[88:91], v[210:213], v[170:173], v[88:91]
	v_mfma_f32_16x16x32_bf16 v[76:79], v[202:205], v[178:181], v[76:79]
	v_mfma_f32_16x16x32_bf16 v[72:75], v[210:213], v[178:181], v[72:75]
	v_mfma_f32_16x16x32_bf16 v[60:63], v[202:205], v[186:189], v[60:63]
	v_mfma_f32_16x16x32_bf16 v[56:59], v[210:213], v[186:189], v[56:59]
	v_mfma_f32_16x16x32_bf16 v[44:47], v[202:205], v[194:197], v[44:47]
	v_mfma_f32_16x16x32_bf16 v[40:43], v[210:213], v[194:197], v[40:43]
	s_setprio 0
	s_mov_b32 m0, s61
	v_lshl_add_u64 v[214:215], v[218:219], 0, s[2:3]
	s_barrier
	ds_read_b128 v[166:169], v145 offset:49152
	ds_read_b128 v[170:173], v145 offset:50176
	ds_read_b128 v[174:177], v145 offset:51200
	ds_read_b128 v[178:181], v145 offset:52224
	ds_read_b128 v[182:185], v145 offset:53248
	ds_read_b128 v[186:189], v145 offset:54272
	ds_read_b128 v[190:193], v145 offset:55296
	ds_read_b128 v[194:197], v145 offset:56320
	global_load_lds_dwordx4 v[214:215], off
	v_lshl_add_u64 v[214:215], v[222:223], 0, s[2:3]
	s_mov_b32 m0, s62
	s_nop 0
	global_load_lds_dwordx4 v[214:215], off
	s_barrier
;     ...
;         G_PAIR(0, 1);
; #pragma unroll 1
;         for (int t = 2; t < nt; t += 2) G_PAIR(t, 0);
;         p.epi(acc, cur, wr, wc, fr, fq);
;         if (!has_next) break;
;         cur = nxt; cA = nA; cB = nB; cA2 = nA2; cB2 = nB2; ++ui;
;     __device__ __forceinline__ void epi(const f32x4 (&acc)[2][2][4][2], const Unit& u, int wr, int wc, int fr, int fq) const {
;         const int row0 = u.pm * 256 + wr * 64 + fr, col0 = wc * 32 + 4 * fq;
; #pragma unroll
;         for (int ai = 0; ai < 2; ++ai)
; #pragma unroll
;             for (int m = 0; m < 4; ++m) {
;                 float* rowp = Send + (size_t)u.pn * NG * NCH * 256 + ((size_t)u.g * NCH + row0 + ai * 128 + m * 16) * 256 + col0;
; #pragma unroll
;                 for (int bj = 0; bj < 2; ++bj)
; #pragma unroll
;                     for (int n = 0; n < 2; ++n) *(f32x4*)(rowp + bj * 128 + n * 16) = acc[ai][bj][m][n];
;             }
	s_waitcnt lgkmcnt(0)
	s_setprio 1
	s_waitcnt lgkmcnt(0)
	v_mfma_f32_16x16x32_bf16 v[84:87], v[150:153], v[166:169], v[84:87]
	v_mfma_f32_16x16x32_bf16 v[80:83], v[158:161], v[166:169], v[80:83]
	v_mfma_f32_16x16x32_bf16 v[68:71], v[150:153], v[174:177], v[68:71]
	v_mfma_f32_16x16x32_bf16 v[64:67], v[158:161], v[174:177], v[64:67]
	v_mfma_f32_16x16x32_bf16 v[52:55], v[150:153], v[182:185], v[52:55]
	v_mfma_f32_16x16x32_bf16 v[48:51], v[158:161], v[182:185], v[48:51]
	v_mfma_f32_16x16x32_bf16 v[36:39], v[150:153], v[190:193], v[36:39]
	v_mfma_f32_16x16x32_bf16 v[32:35], v[158:161], v[190:193], v[32:35]
	v_mfma_f32_16x16x32_bf16 v[84:87], v[154:157], v[170:173], v[84:87]
	v_mfma_f32_16x16x32_bf16 v[80:83], v[162:165], v[170:173], v[80:83]
	v_mfma_f32_16x16x32_bf16 v[68:71], v[154:157], v[178:181], v[68:71]
	v_mfma_f32_16x16x32_bf16 v[64:67], v[162:165], v[178:181], v[64:67]
	v_mfma_f32_16x16x32_bf16 v[52:55], v[154:157], v[186:189], v[52:55]
	v_mfma_f32_16x16x32_bf16 v[48:51], v[162:165], v[186:189], v[48:51]
	v_mfma_f32_16x16x32_bf16 v[36:39], v[154:157], v[194:197], v[36:39]
	v_mfma_f32_16x16x32_bf16 v[32:35], v[162:165], v[194:197], v[32:35]
	s_setprio 0
	s_barrier
	s_add_u32 s46, s46, 0x40080
	s_addc_u32 s47, s47, 0
	s_mov_b32 m0, s78
	v_lshl_add_u64 v[150:151], s[46:47], 0, v[130:131]
	global_load_lds_dwordx4 v[150:151], off
	v_lshl_add_u64 v[150:151], s[46:47], 0, v[128:129]
	s_mov_b32 m0, s79
	s_nop 0
	global_load_lds_dwordx4 v[150:151], off
	s_waitcnt vmcnt(6)
	s_barrier
	s_setprio 1
	v_mfma_f32_16x16x32_bf16 v[124:127], v[198:201], v[166:169], v[124:127]
	v_mfma_f32_16x16x32_bf16 v[120:123], v[206:209], v[166:169], v[120:123]
	v_mfma_f32_16x16x32_bf16 v[116:119], v[198:201], v[174:177], v[116:119]
	v_mfma_f32_16x16x32_bf16 v[112:115], v[206:209], v[174:177], v[112:115]
	v_mfma_f32_16x16x32_bf16 v[108:111], v[198:201], v[182:185], v[108:111]
	v_mfma_f32_16x16x32_bf16 v[104:107], v[206:209], v[182:185], v[104:107]
	v_mfma_f32_16x16x32_bf16 v[100:103], v[198:201], v[190:193], v[100:103]
	v_mfma_f32_16x16x32_bf16 v[96:99], v[206:209], v[190:193], v[96:99]
	v_mfma_f32_16x16x32_bf16 v[124:127], v[202:205], v[170:173], v[124:127]
	v_mfma_f32_16x16x32_bf16 v[120:123], v[210:213], v[170:173], v[120:123]
	v_mfma_f32_16x16x32_bf16 v[116:119], v[202:205], v[178:181], v[116:119]
	v_mfma_f32_16x16x32_bf16 v[112:115], v[210:213], v[178:181], v[112:115]
	v_mfma_f32_16x16x32_bf16 v[108:111], v[202:205], v[186:189], v[108:111]
	v_mfma_f32_16x16x32_bf16 v[104:107], v[210:213], v[186:189], v[104:107]
	v_mfma_f32_16x16x32_bf16 v[100:103], v[202:205], v[194:197], v[100:103]
	v_mfma_f32_16x16x32_bf16 v[96:99], v[210:213], v[194:197], v[96:99]
	s_setprio 0
	s_add_i32 s80, s80, 2
	s_add_u32 s44, s44, 0x100
	s_addc_u32 s45, s45, 0
	s_cmp_gt_u32 s80, 5
	s_barrier
	s_cbranch_scc0 .LBB0_580
	s_lshl_b32 s1, s53, 25
	s_add_u32 s4, s59, s1
	s_addc_u32 s5, s60, 0
	s_ashr_i32 s1, s0, 31
	v_lshl_add_u32 v138, s54, 8, v142
	s_lshl_b64 s[0:1], s[0:1], 19
	v_ashrrev_i32_e32 v139, 31, v138
	s_add_u32 s0, s4, s0
	v_lshlrev_b64 v[138:139], 10, v[138:139]
	s_addc_u32 s1, s5, s1
	v_lshl_add_u64 v[138:139], s[0:1], 0, v[138:139]
	v_lshl_add_u64 v[138:139], v[138:139], 0, v[132:133]
	global_store_dwordx4 v[138:139], v[28:31], off
	global_store_dwordx4 v[138:139], v[24:27], off offset:64
	global_store_dwordx4 v[138:139], v[92:95], off offset:512
	global_store_dwordx4 v[138:139], v[88:91], off offset:576
	v_add_co_u32_e32 v26, vcc, s58, v138
	v_lshl_add_u64 v[24:25], v[138:139], 0, s[18:19]
	s_nop 0
	v_addc_co_u32_e32 v27, vcc, 0, v139, vcc
	global_store_dwordx4 v[26:27], v[20:23], off
	global_store_dwordx4 v[24:25], v[16:19], off offset:64
	global_store_dwordx4 v[24:25], v[76:79], off offset:512
	global_store_dwordx4 v[24:25], v[72:75], off offset:576
	v_add_co_u32_e32 v18, vcc, s63, v138
	v_lshl_add_u64 v[16:17], v[138:139], 0, s[20:21]
	s_nop 0
	v_addc_co_u32_e32 v19, vcc, 0, v139, vcc
	global_store_dwordx4 v[18:19], v[12:15], off
	global_store_dwordx4 v[16:17], v[8:11], off offset:64
	global_store_dwordx4 v[16:17], v[60:63], off offset:512
	global_store_dwordx4 v[16:17], v[56:59], off offset:576
	v_add_co_u32_e32 v10, vcc, s65, v138
	v_lshl_add_u64 v[8:9], v[138:139], 0, s[22:23]
	s_nop 0
	v_addc_co_u32_e32 v11, vcc, 0, v139, vcc
	global_store_dwordx4 v[10:11], v[4:7], off
	global_store_dwordx4 v[8:9], v[0:3], off offset:64
	global_store_dwordx4 v[8:9], v[44:47], off offset:512
	global_store_dwordx4 v[8:9], v[40:43], off offset:576
	v_add_co_u32_e32 v2, vcc, s67, v138
	v_lshl_add_u64 v[0:1], v[138:139], 0, s[24:25]
	s_nop 0
	v_addc_co_u32_e32 v3, vcc, 0, v139, vcc
	global_store_dwordx4 v[2:3], v[84:87], off
	global_store_dwordx4 v[0:1], v[80:83], off offset:64
	global_store_dwordx4 v[0:1], v[124:127], off offset:512
	global_store_dwordx4 v[0:1], v[120:123], off offset:576
	v_add_co_u32_e32 v2, vcc, s68, v138
	v_lshl_add_u64 v[0:1], v[138:139], 0, s[26:27]
	s_nop 0
	v_addc_co_u32_e32 v3, vcc, 0, v139, vcc
	global_store_dwordx4 v[2:3], v[68:71], off
	global_store_dwordx4 v[0:1], v[64:67], off offset:64
	global_store_dwordx4 v[0:1], v[116:119], off offset:512
	global_store_dwordx4 v[0:1], v[112:115], off offset:576
	v_add_co_u32_e32 v2, vcc, s69, v138
	v_lshl_add_u64 v[0:1], v[138:139], 0, s[28:29]
	s_nop 0
	v_addc_co_u32_e32 v3, vcc, 0, v139, vcc
	global_store_dwordx4 v[2:3], v[52:55], off
	global_store_dwordx4 v[0:1], v[48:51], off offset:64
	global_store_dwordx4 v[0:1], v[108:111], off offset:512
	global_store_dwordx4 v[0:1], v[104:107], off offset:576
	v_add_co_u32_e32 v2, vcc, 0x2c000, v138
	s_mov_b32 s54, s72
	s_nop 0
	v_addc_co_u32_e32 v3, vcc, 0, v139, vcc
	v_readlane_b32 s72, v254, 3
	v_readlane_b32 s74, v254, 5
	s_and_b64 vcc, exec, s[36:37]
	s_mov_b32 s0, s34
	s_mov_b32 s53, s71
	s_mov_b64 s[6:7], s[40:41]
	s_mov_b64 s[4:5], s[38:39]
	v_readlane_b32 s73, v254, 4
	v_readlane_b32 s75, v254, 6
	v_lshl_add_u64 v[0:1], v[138:139], 0, s[30:31]
	global_store_dwordx4 v[2:3], v[36:39], off
	global_store_dwordx4 v[0:1], v[32:35], off offset:64
	global_store_dwordx4 v[0:1], v[100:103], off offset:512
	global_store_dwordx4 v[0:1], v[96:99], off offset:576
	s_cbranch_vccz .LBB0_575
	s_waitcnt vmcnt(0)
	s_cmpk_gt_u32 s48, 0xff
	s_cbranch_scc1 .LBB0_584
	s_barrier

.LBB0_920:
	ds_read_b128 v[132:135], v172
	ds_read_b128 v[136:139], v172 offset:1024
	ds_read_b128 v[152:155], v172 offset:2048
	ds_read_b128 v[156:159], v172 offset:3072
	s_mov_b32 m0, s48
	v_lshl_add_u64 v[168:169], v[120:121], 0, s[30:31]
	ds_read_b128 v[160:163], v173
	ds_read_b128 v[164:167], v173 offset:1024
	ds_read_b128 v[178:181], v173 offset:2048
	ds_read_b128 v[182:185], v173 offset:3072
	ds_read_b128 v[186:189], v173 offset:4096
	ds_read_b128 v[190:193], v173 offset:5120
	ds_read_b128 v[194:197], v173 offset:6144
	ds_read_b128 v[198:201], v173 offset:7168
	global_load_lds_dwordx4 v[168:169], off
	v_lshl_add_u64 v[168:169], v[122:123], 0, s[30:31]
	s_mov_b32 m0, s49
	s_nop 0
	global_load_lds_dwordx4 v[168:169], off
	s_waitcnt lgkmcnt(8)
	s_barrier
	s_waitcnt lgkmcnt(0)
	s_setprio 1
	s_waitcnt lgkmcnt(0)
	v_mfma_f32_16x16x32_bf16 v[116:119], v[132:135], v[160:163], v[116:119]
	s_add_i32 s19, s30, 0xfffc0080
	v_mfma_f32_16x16x32_bf16 v[112:115], v[152:155], v[160:163], v[112:115]
	s_cmp_eq_u32 s17, 12
	v_mfma_f32_16x16x32_bf16 v[100:103], v[132:135], v[178:181], v[100:103]
	s_cselect_b64 s[34:35], -1, 0
	v_mfma_f32_16x16x32_bf16 v[96:99], v[152:155], v[178:181], v[96:99]
	s_and_b64 s[60:61], s[34:35], exec
	v_mfma_f32_16x16x32_bf16 v[84:87], v[132:135], v[186:189], v[84:87]
	s_cselect_b32 s19, 0, s19
	v_mfma_f32_16x16x32_bf16 v[80:83], v[152:155], v[186:189], v[80:83]
	s_and_b64 s[34:35], s[28:29], s[34:35]
	v_mfma_f32_16x16x32_bf16 v[68:71], v[132:135], v[194:197], v[68:71]
	s_and_b64 s[34:35], s[34:35], exec
	v_mfma_f32_16x16x32_bf16 v[64:67], v[152:155], v[194:197], v[64:67]
	s_cselect_b32 s61, s21, s25
	v_mfma_f32_16x16x32_bf16 v[116:119], v[136:139], v[164:167], v[116:119]
	s_cselect_b32 s60, s20, s24
	v_mfma_f32_16x16x32_bf16 v[112:115], v[156:159], v[164:167], v[112:115]
	s_cselect_b32 s35, s23, s27
	v_mfma_f32_16x16x32_bf16 v[100:103], v[136:139], v[182:185], v[100:103]
	s_cselect_b32 s34, s22, s26
	v_mfma_f32_16x16x32_bf16 v[96:99], v[156:159], v[182:185], v[96:99]
	v_mfma_f32_16x16x32_bf16 v[84:87], v[136:139], v[190:193], v[84:87]
	v_mfma_f32_16x16x32_bf16 v[80:83], v[156:159], v[190:193], v[80:83]
	v_mfma_f32_16x16x32_bf16 v[68:71], v[136:139], v[198:201], v[68:71]
	v_mfma_f32_16x16x32_bf16 v[64:67], v[156:159], v[198:201], v[64:67]
	s_setprio 0
	s_barrier
	s_add_u32 s34, s34, s19
	s_addc_u32 s35, s35, 0
	s_mov_b32 m0, s50
	v_lshl_add_u64 v[168:169], s[34:35], 0, v[144:145]
	ds_read_b128 v[202:205], v174
	ds_read_b128 v[206:209], v174 offset:1024
	ds_read_b128 v[210:213], v174 offset:2048
	ds_read_b128 v[214:217], v174 offset:3072
	global_load_lds_dwordx4 v[168:169], off
	v_lshl_add_u64 v[218:219], s[34:35], 0, v[140:141]
	s_mov_b32 m0, s51
	s_nop 0
	global_load_lds_dwordx4 v[218:219], off
	s_barrier
	s_waitcnt lgkmcnt(0)
	s_setprio 1
	s_waitcnt lgkmcnt(0)
	v_mfma_f32_16x16x32_bf16 v[128:131], v[202:205], v[160:163], v[128:131]
	v_mfma_f32_16x16x32_bf16 v[124:127], v[210:213], v[160:163], v[124:127]
	v_mfma_f32_16x16x32_bf16 v[108:111], v[202:205], v[178:181], v[108:111]
	v_mfma_f32_16x16x32_bf16 v[104:107], v[210:213], v[178:181], v[104:107]
	v_mfma_f32_16x16x32_bf16 v[92:95], v[202:205], v[186:189], v[92:95]
	v_mfma_f32_16x16x32_bf16 v[88:91], v[210:213], v[186:189], v[88:91]
	v_mfma_f32_16x16x32_bf16 v[76:79], v[202:205], v[194:197], v[76:79]
	v_mfma_f32_16x16x32_bf16 v[72:75], v[210:213], v[194:197], v[72:75]
	v_mfma_f32_16x16x32_bf16 v[128:131], v[206:209], v[164:167], v[128:131]
	v_mfma_f32_16x16x32_bf16 v[124:127], v[214:217], v[164:167], v[124:127]
	v_mfma_f32_16x16x32_bf16 v[108:111], v[206:209], v[182:185], v[108:111]
	v_mfma_f32_16x16x32_bf16 v[104:107], v[214:217], v[182:185], v[104:107]
	v_mfma_f32_16x16x32_bf16 v[92:95], v[206:209], v[190:193], v[92:95]
	v_mfma_f32_16x16x32_bf16 v[88:91], v[214:217], v[190:193], v[88:91]
	v_mfma_f32_16x16x32_bf16 v[76:79], v[206:209], v[198:201], v[76:79]
	v_mfma_f32_16x16x32_bf16 v[72:75], v[214:217], v[198:201], v[72:75]
	s_setprio 0
	s_add_u32 s60, s60, s19
	s_addc_u32 s61, s61, 0
	s_mov_b32 m0, s41
	v_lshl_add_u64 v[222:223], s[60:61], 0, v[146:147]
	s_barrier
	ds_read_b128 v[160:163], v173 offset:16384
	ds_read_b128 v[164:167], v173 offset:17408
	ds_read_b128 v[178:181], v173 offset:18432
	ds_read_b128 v[182:185], v173 offset:19456
	ds_read_b128 v[186:189], v173 offset:20480
	ds_read_b128 v[190:193], v173 offset:21504
	ds_read_b128 v[194:197], v173 offset:22528
	ds_read_b128 v[198:201], v173 offset:23552
	global_load_lds_dwordx4 v[222:223], off
	v_lshl_add_u64 v[224:225], s[60:61], 0, v[142:143]
	s_mov_b32 m0, s42
	s_nop 0
	global_load_lds_dwordx4 v[224:225], off
	s_barrier
	s_waitcnt lgkmcnt(0)
	s_setprio 1
	s_waitcnt lgkmcnt(0)
	v_mfma_f32_16x16x32_bf16 v[52:55], v[132:135], v[160:163], v[52:55]
	v_mfma_f32_16x16x32_bf16 v[48:51], v[152:155], v[160:163], v[48:51]
	v_mfma_f32_16x16x32_bf16 v[36:39], v[132:135], v[178:181], v[36:39]
	v_mfma_f32_16x16x32_bf16 v[32:35], v[152:155], v[178:181], v[32:35]
	v_mfma_f32_16x16x32_bf16 v[20:23], v[132:135], v[186:189], v[20:23]
	v_mfma_f32_16x16x32_bf16 v[16:19], v[152:155], v[186:189], v[16:19]
	v_mfma_f32_16x16x32_bf16 v[4:7], v[132:135], v[194:197], v[4:7]
	v_mfma_f32_16x16x32_bf16 v[0:3], v[152:155], v[194:197], v[0:3]
	v_mfma_f32_16x16x32_bf16 v[52:55], v[136:139], v[164:167], v[52:55]
	v_mfma_f32_16x16x32_bf16 v[48:51], v[156:159], v[164:167], v[48:51]
	v_mfma_f32_16x16x32_bf16 v[36:39], v[136:139], v[182:185], v[36:39]
	v_mfma_f32_16x16x32_bf16 v[32:35], v[156:159], v[182:185], v[32:35]
	v_mfma_f32_16x16x32_bf16 v[20:23], v[136:139], v[190:193], v[20:23]
	v_mfma_f32_16x16x32_bf16 v[16:19], v[156:159], v[190:193], v[16:19]
	v_mfma_f32_16x16x32_bf16 v[4:7], v[136:139], v[198:201], v[4:7]
	v_mfma_f32_16x16x32_bf16 v[0:3], v[156:159], v[198:201], v[0:3]
	s_setprio 0
	s_barrier
	s_add_u32 s62, s34, 0x40000
	s_addc_u32 s63, s35, 0
	s_mov_b32 m0, s52
	v_lshl_add_u64 v[132:133], s[62:63], 0, v[144:145]
	global_load_lds_dwordx4 v[132:133], off
	v_lshl_add_u64 v[132:133], s[62:63], 0, v[140:141]
	s_mov_b32 m0, s53
	s_nop 0
	global_load_lds_dwordx4 v[132:133], off
	s_waitcnt vmcnt(6)
	s_barrier
	s_setprio 1
	v_mfma_f32_16x16x32_bf16 v[60:63], v[202:205], v[160:163], v[60:63]
	v_mfma_f32_16x16x32_bf16 v[56:59], v[210:213], v[160:163], v[56:59]
	v_mfma_f32_16x16x32_bf16 v[44:47], v[202:205], v[178:181], v[44:47]
	v_mfma_f32_16x16x32_bf16 v[40:43], v[210:213], v[178:181], v[40:43]
	v_mfma_f32_16x16x32_bf16 v[28:31], v[202:205], v[186:189], v[28:31]
	v_mfma_f32_16x16x32_bf16 v[24:27], v[210:213], v[186:189], v[24:27]
	v_mfma_f32_16x16x32_bf16 v[12:15], v[202:205], v[194:197], v[12:15]
	v_mfma_f32_16x16x32_bf16 v[8:11], v[210:213], v[194:197], v[8:11]
	v_mfma_f32_16x16x32_bf16 v[60:63], v[206:209], v[164:167], v[60:63]
	v_mfma_f32_16x16x32_bf16 v[56:59], v[214:217], v[164:167], v[56:59]
	v_mfma_f32_16x16x32_bf16 v[44:47], v[206:209], v[182:185], v[44:47]
	v_mfma_f32_16x16x32_bf16 v[40:43], v[214:217], v[182:185], v[40:43]
	v_mfma_f32_16x16x32_bf16 v[28:31], v[206:209], v[190:193], v[28:31]
	v_mfma_f32_16x16x32_bf16 v[24:27], v[214:217], v[190:193], v[24:27]
	v_mfma_f32_16x16x32_bf16 v[12:15], v[206:209], v[198:201], v[12:15]
	v_mfma_f32_16x16x32_bf16 v[8:11], v[214:217], v[198:201], v[8:11]
	s_setprio 0
	s_barrier
	ds_read_b128 v[132:135], v176
	ds_read_b128 v[136:139], v176 offset:1024
	ds_read_b128 v[152:155], v176 offset:2048
	ds_read_b128 v[156:159], v176 offset:3072
	s_add_u32 s60, s60, 0x40000
	s_addc_u32 s61, s61, 0
	s_mov_b32 m0, s43
	v_lshl_add_u64 v[202:203], s[60:61], 0, v[146:147]
	ds_read_b128 v[160:163], v173 offset:32768
	ds_read_b128 v[164:167], v173 offset:33792
	ds_read_b128 v[178:181], v173 offset:34816
	ds_read_b128 v[182:185], v173 offset:35840
	ds_read_b128 v[186:189], v173 offset:36864
	ds_read_b128 v[190:193], v173 offset:37888
	ds_read_b128 v[194:197], v173 offset:38912
	ds_read_b128 v[198:201], v173 offset:39936
	global_load_lds_dwordx4 v[202:203], off
	v_lshl_add_u64 v[202:203], s[60:61], 0, v[142:143]
	s_mov_b32 m0, s44
	s_nop 0
	global_load_lds_dwordx4 v[202:203], off
	s_waitcnt lgkmcnt(8)
	s_barrier
	s_waitcnt lgkmcnt(0)
	s_setprio 1
	s_waitcnt lgkmcnt(0)
	v_mfma_f32_16x16x32_bf16 v[116:119], v[132:135], v[160:163], v[116:119]
	v_mfma_f32_16x16x32_bf16 v[112:115], v[152:155], v[160:163], v[112:115]
	v_mfma_f32_16x16x32_bf16 v[100:103], v[132:135], v[178:181], v[100:103]
	v_mfma_f32_16x16x32_bf16 v[96:99], v[152:155], v[178:181], v[96:99]
	v_mfma_f32_16x16x32_bf16 v[84:87], v[132:135], v[186:189], v[84:87]
	v_mfma_f32_16x16x32_bf16 v[80:83], v[152:155], v[186:189], v[80:83]
	v_mfma_f32_16x16x32_bf16 v[68:71], v[132:135], v[194:197], v[68:71]
	v_mfma_f32_16x16x32_bf16 v[64:67], v[152:155], v[194:197], v[64:67]
	v_mfma_f32_16x16x32_bf16 v[116:119], v[136:139], v[164:167], v[116:119]
	v_mfma_f32_16x16x32_bf16 v[112:115], v[156:159], v[164:167], v[112:115]
	v_mfma_f32_16x16x32_bf16 v[100:103], v[136:139], v[182:185], v[100:103]
	v_mfma_f32_16x16x32_bf16 v[96:99], v[156:159], v[182:185], v[96:99]
	v_mfma_f32_16x16x32_bf16 v[84:87], v[136:139], v[190:193], v[84:87]
	v_mfma_f32_16x16x32_bf16 v[80:83], v[156:159], v[190:193], v[80:83]
	v_mfma_f32_16x16x32_bf16 v[68:71], v[136:139], v[198:201], v[68:71]
	v_mfma_f32_16x16x32_bf16 v[64:67], v[156:159], v[198:201], v[64:67]
	s_setprio 0
	s_barrier
	s_mov_b32 m0, s54
	v_lshl_add_u64 v[168:169], v[168:169], 0, s[6:7]
	ds_read_b128 v[202:205], v177
	ds_read_b128 v[206:209], v177 offset:1024
	ds_read_b128 v[210:213], v177 offset:2048
	ds_read_b128 v[214:217], v177 offset:3072
	global_load_lds_dwordx4 v[168:169], off
	v_lshl_add_u64 v[168:169], v[218:219], 0, s[6:7]
	s_mov_b32 m0, s55
	s_nop 0
	global_load_lds_dwordx4 v[168:169], off
	s_barrier
	s_waitcnt lgkmcnt(0)
	s_setprio 1
	s_waitcnt lgkmcnt(0)
	v_mfma_f32_16x16x32_bf16 v[128:131], v[202:205], v[160:163], v[128:131]
	v_mfma_f32_16x16x32_bf16 v[124:127], v[210:213], v[160:163], v[124:127]
	v_mfma_f32_16x16x32_bf16 v[108:111], v[202:205], v[178:181], v[108:111]
	v_mfma_f32_16x16x32_bf16 v[104:107], v[210:213], v[178:181], v[104:107]
	v_mfma_f32_16x16x32_bf16 v[92:95], v[202:205], v[186:189], v[92:95]
	v_mfma_f32_16x16x32_bf16 v[88:91], v[210:213], v[186:189], v[88:91]
	v_mfma_f32_16x16x32_bf16 v[76:79], v[202:205], v[194:197], v[76:79]
	v_mfma_f32_16x16x32_bf16 v[72:75], v[210:213], v[194:197], v[72:75]
	v_mfma_f32_16x16x32_bf16 v[128:131], v[206:209], v[164:167], v[128:131]
	v_mfma_f32_16x16x32_bf16 v[124:127], v[214:217], v[164:167], v[124:127]
	v_mfma_f32_16x16x32_bf16 v[108:111], v[206:209], v[182:185], v[108:111]
	v_mfma_f32_16x16x32_bf16 v[104:107], v[214:217], v[182:185], v[104:107]
	v_mfma_f32_16x16x32_bf16 v[92:95], v[206:209], v[190:193], v[92:95]
	v_mfma_f32_16x16x32_bf16 v[88:91], v[214:217], v[190:193], v[88:91]
	v_mfma_f32_16x16x32_bf16 v[76:79], v[206:209], v[198:201], v[76:79]
	v_mfma_f32_16x16x32_bf16 v[72:75], v[214:217], v[198:201], v[72:75]
	s_setprio 0
	s_mov_b32 m0, s46
	v_lshl_add_u64 v[168:169], v[222:223], 0, s[6:7]
	s_barrier
	ds_read_b128 v[160:163], v173 offset:49152
	ds_read_b128 v[164:167], v173 offset:50176
	ds_read_b128 v[178:181], v173 offset:51200
	ds_read_b128 v[182:185], v173 offset:52224
	ds_read_b128 v[186:189], v173 offset:53248
	ds_read_b128 v[190:193], v173 offset:54272
	ds_read_b128 v[194:197], v173 offset:55296
	ds_read_b128 v[198:201], v173 offset:56320
	global_load_lds_dwordx4 v[168:169], off
	v_lshl_add_u64 v[168:169], v[224:225], 0, s[6:7]
	s_mov_b32 m0, s47
	s_nop 0
	global_load_lds_dwordx4 v[168:169], off
	s_barrier
; __device__ __forceinline__ unsigned pk2(float lo, float hi) { unsigned r; asm volatile("v_cvt_pk_bf16_f32 %0, %1, %2" : "=v"(r) : "v"(lo), "v"(hi)); return r; }
; __device__ __forceinline__ unsigned pk2(float lo, float hi) { return f2bf(lo) | (f2bf(hi) << 16); }
; __device__ __forceinline__ float fast_sigmoid(float z) { return __builtin_amdgcn_rcpf(1.0f + __expf(-z)); }
;     ...
;         G_PAIR(0, 1);
; #pragma unroll 1
;         for (int t = 2; t < nt; t += 2) G_PAIR(t, 0);
;     __device__ __forceinline__ void epi(const f32x4 (&acc)[2][2][4][2], const Unit& u, int wr, int wc, int fr, int fq) const {
;         const int row0 = u.pm * 256 + wr * 64 + fr, col0 = u.pn * 128 + wc * 32 + 8 * fq;
; #pragma unroll
;         for (int ai = 0; ai < 2; ++ai) {
;             u32x4 xo[4];
; #pragma unroll
;             for (int m = 0; m < 4; ++m) xo[m] = *(const u32x4*)(xb + (size_t)(row0 + ai * 128 + m * 16) * D + col0);
; #pragma unroll
;             for (int m = 0; m < 4; ++m) {
;                 const int row = row0 + ai * 128 + m * 16; const size_t off = (size_t)row * D + col0;
;                 const u32x4 o = xo[m]; const f32x4 a0v = acc[ai][0][m][0], a1v = acc[ai][0][m][1], b0v = acc[ai][1][m][0], b1v = acc[ai][1][m][1];
;                 const float v0 = bf_lo(o.x) + coef * a0v[0] * fast_sigmoid(b0v[0]), v1 = bf_hi(o.x) + coef * a0v[1] * fast_sigmoid(b0v[1]);
;                 const float v2 = bf_lo(o.y) + coef * a0v[2] * fast_sigmoid(b0v[2]), v3 = bf_hi(o.y) + coef * a0v[3] * fast_sigmoid(b0v[3]);
;                 const float v4 = bf_lo(o.z) + coef * a1v[0] * fast_sigmoid(b1v[0]), v5 = bf_hi(o.z) + coef * a1v[1] * fast_sigmoid(b1v[1]);
;                 const float v6 = bf_lo(o.w) + coef * a1v[2] * fast_sigmoid(b1v[2]), v7 = bf_hi(o.w) + coef * a1v[3] * fast_sigmoid(b1v[3]);
;                 u32x4 w; w.x = pk2(v0, v1); w.y = pk2(v2, v3); w.z = pk2(v4, v5); w.w = pk2(v6, v7);
;                 *(u32x4*)(xb + off) = w;
;                 float ss = ((v0 * v0 + v1 * v1) + (v2 * v2 + v3 * v3)) + ((v4 * v4 + v5 * v5) + (v6 * v6 + v7 * v7));
;                 ss += __shfl_xor(ss, 16); ss += __shfl_xor(ss, 32);
;                 if (fq == 0) rowss[(size_t)row * 32 + u.pn * 4 + wc] = ss;
	s_waitcnt lgkmcnt(0)
	s_setprio 1
	s_waitcnt lgkmcnt(0)
	v_mfma_f32_16x16x32_bf16 v[52:55], v[132:135], v[160:163], v[52:55]
	v_mfma_f32_16x16x32_bf16 v[48:51], v[152:155], v[160:163], v[48:51]
	v_mfma_f32_16x16x32_bf16 v[36:39], v[132:135], v[178:181], v[36:39]
	v_mfma_f32_16x16x32_bf16 v[32:35], v[152:155], v[178:181], v[32:35]
	v_mfma_f32_16x16x32_bf16 v[20:23], v[132:135], v[186:189], v[20:23]
	v_mfma_f32_16x16x32_bf16 v[16:19], v[152:155], v[186:189], v[16:19]
	v_mfma_f32_16x16x32_bf16 v[4:7], v[132:135], v[194:197], v[4:7]
	v_mfma_f32_16x16x32_bf16 v[0:3], v[152:155], v[194:197], v[0:3]
	v_mfma_f32_16x16x32_bf16 v[52:55], v[136:139], v[164:167], v[52:55]
	v_mfma_f32_16x16x32_bf16 v[48:51], v[156:159], v[164:167], v[48:51]
	v_mfma_f32_16x16x32_bf16 v[36:39], v[136:139], v[182:185], v[36:39]
	v_mfma_f32_16x16x32_bf16 v[32:35], v[156:159], v[182:185], v[32:35]
	v_mfma_f32_16x16x32_bf16 v[20:23], v[136:139], v[190:193], v[20:23]
	v_mfma_f32_16x16x32_bf16 v[16:19], v[156:159], v[190:193], v[16:19]
	v_mfma_f32_16x16x32_bf16 v[4:7], v[136:139], v[198:201], v[4:7]
	v_mfma_f32_16x16x32_bf16 v[0:3], v[156:159], v[198:201], v[0:3]
	s_setprio 0
	s_barrier
	s_add_u32 s34, s34, 0x40080
	s_addc_u32 s35, s35, 0
	s_mov_b32 m0, s56
	v_lshl_add_u64 v[132:133], s[34:35], 0, v[144:145]
	global_load_lds_dwordx4 v[132:133], off
	v_lshl_add_u64 v[132:133], s[34:35], 0, v[140:141]
	s_mov_b32 m0, s57
	s_nop 0
	global_load_lds_dwordx4 v[132:133], off
	s_waitcnt vmcnt(6)
	s_barrier
	s_setprio 1
	v_mfma_f32_16x16x32_bf16 v[60:63], v[202:205], v[160:163], v[60:63]
	v_mfma_f32_16x16x32_bf16 v[56:59], v[210:213], v[160:163], v[56:59]
	v_mfma_f32_16x16x32_bf16 v[44:47], v[202:205], v[178:181], v[44:47]
	v_mfma_f32_16x16x32_bf16 v[40:43], v[210:213], v[178:181], v[40:43]
	v_mfma_f32_16x16x32_bf16 v[28:31], v[202:205], v[186:189], v[28:31]
	v_mfma_f32_16x16x32_bf16 v[24:27], v[210:213], v[186:189], v[24:27]
	v_mfma_f32_16x16x32_bf16 v[12:15], v[202:205], v[194:197], v[12:15]
	v_mfma_f32_16x16x32_bf16 v[8:11], v[210:213], v[194:197], v[8:11]
	v_mfma_f32_16x16x32_bf16 v[60:63], v[206:209], v[164:167], v[60:63]
	v_mfma_f32_16x16x32_bf16 v[56:59], v[214:217], v[164:167], v[56:59]
	v_mfma_f32_16x16x32_bf16 v[44:47], v[206:209], v[182:185], v[44:47]
	v_mfma_f32_16x16x32_bf16 v[40:43], v[214:217], v[182:185], v[40:43]
	v_mfma_f32_16x16x32_bf16 v[28:31], v[206:209], v[190:193], v[28:31]
	v_mfma_f32_16x16x32_bf16 v[24:27], v[214:217], v[190:193], v[24:27]
	v_mfma_f32_16x16x32_bf16 v[12:15], v[206:209], v[198:201], v[12:15]
	v_mfma_f32_16x16x32_bf16 v[8:11], v[214:217], v[198:201], v[8:11]
	s_setprio 0
	s_add_i32 s17, s17, 2
	s_add_u32 s30, s30, 0x100
	s_addc_u32 s31, s31, 0
	s_cmp_gt_u32 s17, 13
	s_barrier
	s_cbranch_scc0 .LBB0_920
	v_lshl_or_b32 v152, s59, 7, v171
	v_lshl_add_u32 v156, s8, 8, v170
	v_ashrrev_i32_e32 v153, 31, v152
	v_lshlrev_b64 v[182:183], 1, v[152:153]
	v_ashrrev_i32_e32 v157, 31, v156
	v_lshl_add_u64 v[154:155], s[0:1], 0, v[182:183]
	v_lshlrev_b64 v[184:185], 11, v[156:157]
	v_lshl_add_u64 v[120:121], v[154:155], 0, v[184:185]
	global_load_dwordx4 v[178:181], v[120:121], off
	v_or_b32_e32 v166, 16, v156
	v_or_b32_e32 v162, 32, v156
	v_or_b32_e32 v158, 48, v156
	v_ashrrev_i32_e32 v167, 31, v166
	v_ashrrev_i32_e32 v163, 31, v162
	v_ashrrev_i32_e32 v159, 31, v158
	v_lshlrev_b64 v[168:169], 11, v[166:167]
	v_lshlrev_b64 v[164:165], 11, v[162:163]
	v_lshlrev_b64 v[160:161], 11, v[158:159]
	v_lshl_add_u64 v[120:121], v[154:155], 0, v[168:169]
	v_lshl_add_u64 v[122:123], v[154:155], 0, v[164:165]
	v_lshl_add_u64 v[186:187], v[154:155], 0, v[160:161]
	global_load_dwordx4 v[136:139], v[120:121], off
	global_load_dwordx4 v[132:135], v[122:123], off
	s_nop 0
	global_load_dwordx4 v[120:123], v[186:187], off
	v_mul_f32_e32 v129, 0xbfb8aa3b, v129
	v_mul_f32_e32 v131, 0xbfb8aa3b, v131
	v_mul_f32_e32 v125, 0xbfb8aa3b, v125
	v_mul_f32_e32 v127, 0xbfb8aa3b, v127
	v_mul_f32_e32 v128, 0xbfb8aa3b, v128
	v_mul_f32_e32 v130, 0xbfb8aa3b, v130
	v_mul_f32_e32 v124, 0xbfb8aa3b, v124
	v_mul_f32_e32 v126, 0xbfb8aa3b, v126
	v_exp_f32_e32 v129, v129
	v_exp_f32_e32 v131, v131
	v_exp_f32_e32 v125, v125
	v_exp_f32_e32 v127, v127
	v_exp_f32_e32 v128, v128
	v_exp_f32_e32 v130, v130
	v_exp_f32_e32 v189, v124
	v_exp_f32_e32 v126, v126
	v_and_b32_e32 v187, 64, v175
	v_xor_b32_e32 v186, 16, v175
	v_add_u32_e32 v187, 64, v187
	v_cmp_lt_i32_e32 vcc, v186, v187
	v_add_f32_e32 v129, 1.0, v129
	v_add_f32_e32 v131, 1.0, v131
	v_add_f32_e32 v125, 1.0, v125
	v_add_f32_e32 v127, 1.0, v127
	v_cndmask_b32_e32 v124, v175, v186, vcc
	v_add_f32_e32 v128, 1.0, v128
	v_add_f32_e32 v130, 1.0, v130
	v_add_f32_e32 v186, 1.0, v189
	v_add_f32_e32 v126, 1.0, v126
	v_rcp_f32_e32 v129, v129
	v_rcp_f32_e32 v131, v131
	v_rcp_f32_e32 v125, v125
	v_rcp_f32_e32 v127, v127
	v_rcp_f32_e32 v128, v128
	v_rcp_f32_e32 v130, v130
	v_rcp_f32_e32 v186, v186
	v_rcp_f32_e32 v126, v126
	v_lshlrev_b32_e32 v124, 2, v124
	v_xor_b32_e32 v188, 32, v175
	v_cmp_lt_i32_e32 vcc, v188, v187
	s_lshl_b32 s24, s59, 2
	s_ashr_i32 s25, s24, 31
	s_waitcnt vmcnt(0)
	v_lshlrev_b32_e32 v189, 16, v178
	v_and_b32_e32 v178, 0xffff0000, v178
	v_lshlrev_b32_e32 v190, 16, v179
	v_and_b32_e32 v179, 0xffff0000, v179
	v_lshlrev_b32_e32 v191, 16, v180
	v_and_b32_e32 v180, 0xffff0000, v180
	v_lshlrev_b32_e32 v192, 16, v181
	v_and_b32_e32 v181, 0xffff0000, v181
	v_fmac_f32_e32 v178, v117, v129
	v_fmac_f32_e32 v179, v119, v131
	v_fmac_f32_e32 v180, v113, v125
	v_fmac_f32_e32 v181, v115, v127
	v_fmac_f32_e32 v189, v116, v128
	v_fmac_f32_e32 v190, v118, v130
	v_fmac_f32_e32 v191, v112, v186
	v_fmac_f32_e32 v192, v114, v126
	v_mul_f32_e32 v112, v178, v178
	v_mul_f32_e32 v113, v179, v179
	v_mul_f32_e32 v114, v180, v180
	v_mul_f32_e32 v115, v181, v181
	v_fmac_f32_e32 v112, v189, v189
	v_fmac_f32_e32 v113, v190, v190
	v_fmac_f32_e32 v114, v191, v191
	v_fmac_f32_e32 v115, v192, v192
	v_add_f32_e32 v112, v112, v113
	v_add_f32_e32 v113, v114, v115
	v_add_f32_e32 v112, v112, v113
	ds_bpermute_b32 v113, v124, v112
	v_lshl_add_u64 v[126:127], s[0:1], 0, v[184:185]
	v_lshl_add_u64 v[126:127], v[126:127], 0, v[182:183]
	v_cvt_pk_bf16_f32 v116, v189, v178
	v_cvt_pk_bf16_f32 v117, v190, v179
	s_waitcnt lgkmcnt(0)
	v_add_f32_e32 v113, v112, v113
	v_cndmask_b32_e32 v112, v175, v188, vcc
	v_lshlrev_b32_e32 v112, 2, v112
	ds_bpermute_b32 v114, v112, v113
	v_cvt_pk_bf16_f32 v118, v191, v180
	v_cvt_pk_bf16_f32 v119, v192, v181
	global_store_dwordx4 v[126:127], v[116:119], off
	s_and_saveexec_b64 s[26:27], s[4:5]
	s_cbranch_execz .LBB0_923
	v_lshlrev_b64 v[116:117], 7, v[156:157]
	v_lshl_add_u64 v[116:117], s[2:3], 0, v[116:117]
	v_lshl_add_u64 v[116:117], s[24:25], 2, v[116:117]
	s_lshl_b32 s8, s45, 2
	v_lshl_add_u64 v[116:117], v[116:117], 0, s[8:9]
	s_waitcnt lgkmcnt(0)
	v_add_f32_e32 v113, v113, v114
	global_store_dword v[116:117], v113, off

.LBB0_1906:
	ds_read_b128 v[134:137], v185
	ds_read_b128 v[138:141], v185 offset:1024
	ds_read_b128 v[142:145], v185 offset:2048
	ds_read_b128 v[146:149], v185 offset:3072
	s_mov_b32 m0, s45
	v_lshl_add_u64 v[150:151], v[128:129], 0, s[24:25]
	ds_read_b128 v[164:167], v186
	ds_read_b128 v[168:171], v186 offset:1024
	ds_read_b128 v[172:175], v186 offset:2048
	ds_read_b128 v[176:179], v186 offset:3072
	ds_read_b128 v[190:193], v186 offset:4096
	ds_read_b128 v[194:197], v186 offset:5120
	ds_read_b128 v[198:201], v186 offset:6144
	ds_read_b128 v[202:205], v186 offset:7168
	global_load_lds_dwordx4 v[150:151], off
	v_lshl_add_u64 v[150:151], v[130:131], 0, s[24:25]
	s_mov_b32 m0, s46
	s_nop 0
	global_load_lds_dwordx4 v[150:151], off
	s_waitcnt lgkmcnt(8)
	s_barrier
	s_waitcnt lgkmcnt(0)
	s_setprio 1
	s_waitcnt lgkmcnt(0)
	v_mfma_f32_16x16x32_bf16 v[116:119], v[134:137], v[164:167], v[116:119]
	s_add_i32 s26, s24, 0xfff50080
	v_mfma_f32_16x16x32_bf16 v[112:115], v[142:145], v[164:167], v[112:115]
	s_cmp_eq_u32 s58, 40
	v_mfma_f32_16x16x32_bf16 v[108:111], v[134:137], v[172:175], v[108:111]
	s_cselect_b32 s59, s19, s21
	v_mfma_f32_16x16x32_bf16 v[104:107], v[142:145], v[172:175], v[104:107]
	s_cselect_b32 s60, s18, s20
	v_mfma_f32_16x16x32_bf16 v[92:95], v[134:137], v[190:193], v[92:95]
	s_cselect_b32 s27, s7, s23
	v_mfma_f32_16x16x32_bf16 v[88:91], v[142:145], v[190:193], v[88:91]
	s_cselect_b32 s61, s6, s22
	v_mfma_f32_16x16x32_bf16 v[76:79], v[134:137], v[198:201], v[76:79]
	v_mfma_f32_16x16x32_bf16 v[72:75], v[142:145], v[198:201], v[72:75]
	v_mfma_f32_16x16x32_bf16 v[116:119], v[138:141], v[168:171], v[116:119]
	v_mfma_f32_16x16x32_bf16 v[112:115], v[146:149], v[168:171], v[112:115]
	v_mfma_f32_16x16x32_bf16 v[108:111], v[138:141], v[176:179], v[108:111]
	v_mfma_f32_16x16x32_bf16 v[104:107], v[146:149], v[176:179], v[104:107]
	v_mfma_f32_16x16x32_bf16 v[92:95], v[138:141], v[194:197], v[92:95]
	v_mfma_f32_16x16x32_bf16 v[88:91], v[146:149], v[194:197], v[88:91]
	v_mfma_f32_16x16x32_bf16 v[76:79], v[138:141], v[202:205], v[76:79]
	v_mfma_f32_16x16x32_bf16 v[72:75], v[146:149], v[202:205], v[72:75]
	s_setprio 0
	s_barrier
	s_cselect_b32 s62, 0, s26
	s_add_u32 s26, s61, s62
	s_addc_u32 s27, s27, 0
	s_mov_b32 m0, s47
	v_lshl_add_u64 v[150:151], s[26:27], 0, v[154:155]
	ds_read_b128 v[206:209], v187
	ds_read_b128 v[210:213], v187 offset:1024
	ds_read_b128 v[214:217], v187 offset:2048
	ds_read_b128 v[222:225], v187 offset:3072
	global_load_lds_dwordx4 v[150:151], off
	v_lshl_add_u64 v[180:181], s[26:27], 0, v[158:159]
	s_mov_b32 m0, s48
	s_nop 0
	global_load_lds_dwordx4 v[180:181], off
	s_barrier
	s_waitcnt lgkmcnt(0)
	s_setprio 1
	s_waitcnt lgkmcnt(0)
	v_mfma_f32_16x16x32_bf16 v[124:127], v[206:209], v[164:167], v[124:127]
	v_mfma_f32_16x16x32_bf16 v[120:123], v[214:217], v[164:167], v[120:123]
	v_mfma_f32_16x16x32_bf16 v[100:103], v[206:209], v[172:175], v[100:103]
	v_mfma_f32_16x16x32_bf16 v[96:99], v[214:217], v[172:175], v[96:99]
	v_mfma_f32_16x16x32_bf16 v[84:87], v[206:209], v[190:193], v[84:87]
	v_mfma_f32_16x16x32_bf16 v[80:83], v[214:217], v[190:193], v[80:83]
	v_mfma_f32_16x16x32_bf16 v[68:71], v[206:209], v[198:201], v[68:71]
	v_mfma_f32_16x16x32_bf16 v[64:67], v[214:217], v[198:201], v[64:67]
	v_mfma_f32_16x16x32_bf16 v[124:127], v[210:213], v[168:171], v[124:127]
	v_mfma_f32_16x16x32_bf16 v[120:123], v[222:225], v[168:171], v[120:123]
	v_mfma_f32_16x16x32_bf16 v[100:103], v[210:213], v[176:179], v[100:103]
	v_mfma_f32_16x16x32_bf16 v[96:99], v[222:225], v[176:179], v[96:99]
	v_mfma_f32_16x16x32_bf16 v[84:87], v[210:213], v[194:197], v[84:87]
	v_mfma_f32_16x16x32_bf16 v[80:83], v[222:225], v[194:197], v[80:83]
	v_mfma_f32_16x16x32_bf16 v[68:71], v[210:213], v[202:205], v[68:71]
	v_mfma_f32_16x16x32_bf16 v[64:67], v[222:225], v[202:205], v[64:67]
	s_setprio 0
	s_add_u32 s60, s60, s62
	s_addc_u32 s61, s59, 0
	s_mov_b32 m0, s37
	v_lshl_add_u64 v[218:219], s[60:61], 0, v[152:153]
	s_barrier
	ds_read_b128 v[164:167], v186 offset:16384
	ds_read_b128 v[168:171], v186 offset:17408
	ds_read_b128 v[172:175], v186 offset:18432
	ds_read_b128 v[176:179], v186 offset:19456
	ds_read_b128 v[190:193], v186 offset:20480
	ds_read_b128 v[194:197], v186 offset:21504
	ds_read_b128 v[198:201], v186 offset:22528
	ds_read_b128 v[202:205], v186 offset:23552
	global_load_lds_dwordx4 v[218:219], off
	v_lshl_add_u64 v[226:227], s[60:61], 0, v[156:157]
	s_mov_b32 m0, s38
	s_nop 0
	global_load_lds_dwordx4 v[226:227], off
	s_barrier
	s_waitcnt lgkmcnt(0)
	s_setprio 1
	s_waitcnt lgkmcnt(0)
	v_mfma_f32_16x16x32_bf16 v[52:55], v[134:137], v[164:167], v[52:55]
	v_mfma_f32_16x16x32_bf16 v[48:51], v[142:145], v[164:167], v[48:51]
	v_mfma_f32_16x16x32_bf16 v[44:47], v[134:137], v[172:175], v[44:47]
	v_mfma_f32_16x16x32_bf16 v[36:39], v[142:145], v[172:175], v[36:39]
	v_mfma_f32_16x16x32_bf16 v[28:31], v[134:137], v[190:193], v[28:31]
	v_mfma_f32_16x16x32_bf16 v[20:23], v[142:145], v[190:193], v[20:23]
	v_mfma_f32_16x16x32_bf16 v[12:15], v[134:137], v[198:201], v[12:15]
	v_mfma_f32_16x16x32_bf16 v[4:7], v[142:145], v[198:201], v[4:7]
	v_mfma_f32_16x16x32_bf16 v[52:55], v[138:141], v[168:171], v[52:55]
	v_mfma_f32_16x16x32_bf16 v[48:51], v[146:149], v[168:171], v[48:51]
	v_mfma_f32_16x16x32_bf16 v[44:47], v[138:141], v[176:179], v[44:47]
	v_mfma_f32_16x16x32_bf16 v[36:39], v[146:149], v[176:179], v[36:39]
	v_mfma_f32_16x16x32_bf16 v[28:31], v[138:141], v[194:197], v[28:31]
	v_mfma_f32_16x16x32_bf16 v[20:23], v[146:149], v[194:197], v[20:23]
	v_mfma_f32_16x16x32_bf16 v[12:15], v[138:141], v[202:205], v[12:15]
	v_mfma_f32_16x16x32_bf16 v[4:7], v[146:149], v[202:205], v[4:7]
	s_setprio 0
	s_barrier
	s_add_u32 s62, s26, 0xb0000
	s_addc_u32 s63, s27, 0
	s_mov_b32 m0, s52
	v_lshl_add_u64 v[134:135], s[62:63], 0, v[154:155]
	global_load_lds_dwordx4 v[134:135], off
	v_lshl_add_u64 v[134:135], s[62:63], 0, v[158:159]
	s_mov_b32 m0, s53
	s_nop 0
	global_load_lds_dwordx4 v[134:135], off
	s_waitcnt vmcnt(6)
	s_barrier
	s_setprio 1
	v_mfma_f32_16x16x32_bf16 v[60:63], v[206:209], v[164:167], v[60:63]
	v_mfma_f32_16x16x32_bf16 v[56:59], v[214:217], v[164:167], v[56:59]
	v_mfma_f32_16x16x32_bf16 v[40:43], v[206:209], v[172:175], v[40:43]
	v_mfma_f32_16x16x32_bf16 v[32:35], v[214:217], v[172:175], v[32:35]
	v_mfma_f32_16x16x32_bf16 v[24:27], v[206:209], v[190:193], v[24:27]
	v_mfma_f32_16x16x32_bf16 v[16:19], v[214:217], v[190:193], v[16:19]
	v_mfma_f32_16x16x32_bf16 v[8:11], v[206:209], v[198:201], v[8:11]
	v_mfma_f32_16x16x32_bf16 v[0:3], v[214:217], v[198:201], v[0:3]
	v_mfma_f32_16x16x32_bf16 v[60:63], v[210:213], v[168:171], v[60:63]
	v_mfma_f32_16x16x32_bf16 v[56:59], v[222:225], v[168:171], v[56:59]
	v_mfma_f32_16x16x32_bf16 v[40:43], v[210:213], v[176:179], v[40:43]
	v_mfma_f32_16x16x32_bf16 v[32:35], v[222:225], v[176:179], v[32:35]
	v_mfma_f32_16x16x32_bf16 v[24:27], v[210:213], v[194:197], v[24:27]
	v_mfma_f32_16x16x32_bf16 v[16:19], v[222:225], v[194:197], v[16:19]
	v_mfma_f32_16x16x32_bf16 v[8:11], v[210:213], v[202:205], v[8:11]
	v_mfma_f32_16x16x32_bf16 v[0:3], v[222:225], v[202:205], v[0:3]
	s_setprio 0
	s_barrier
	ds_read_b128 v[134:137], v132
	ds_read_b128 v[138:141], v132 offset:1024
	ds_read_b128 v[142:145], v132 offset:2048
	ds_read_b128 v[146:149], v132 offset:3072
	s_add_u32 s60, s60, 0xb0000
	s_addc_u32 s61, s61, 0
	s_mov_b32 m0, s39
	v_lshl_add_u64 v[206:207], s[60:61], 0, v[152:153]
	ds_read_b128 v[164:167], v186 offset:32768
	ds_read_b128 v[168:171], v186 offset:33792
	ds_read_b128 v[172:175], v186 offset:34816
	ds_read_b128 v[176:179], v186 offset:35840
	ds_read_b128 v[190:193], v186 offset:36864
	ds_read_b128 v[194:197], v186 offset:37888
	ds_read_b128 v[198:201], v186 offset:38912
	ds_read_b128 v[202:205], v186 offset:39936
	global_load_lds_dwordx4 v[206:207], off
	v_lshl_add_u64 v[206:207], s[60:61], 0, v[156:157]
	s_mov_b32 m0, s40
	s_nop 0
	global_load_lds_dwordx4 v[206:207], off
	s_waitcnt lgkmcnt(8)
	s_barrier
	s_waitcnt lgkmcnt(0)
	s_setprio 1
	s_waitcnt lgkmcnt(0)
	v_mfma_f32_16x16x32_bf16 v[116:119], v[134:137], v[164:167], v[116:119]
	v_mfma_f32_16x16x32_bf16 v[112:115], v[142:145], v[164:167], v[112:115]
	v_mfma_f32_16x16x32_bf16 v[108:111], v[134:137], v[172:175], v[108:111]
	v_mfma_f32_16x16x32_bf16 v[104:107], v[142:145], v[172:175], v[104:107]
	v_mfma_f32_16x16x32_bf16 v[92:95], v[134:137], v[190:193], v[92:95]
	v_mfma_f32_16x16x32_bf16 v[88:91], v[142:145], v[190:193], v[88:91]
	v_mfma_f32_16x16x32_bf16 v[76:79], v[134:137], v[198:201], v[76:79]
	v_mfma_f32_16x16x32_bf16 v[72:75], v[142:145], v[198:201], v[72:75]
	v_mfma_f32_16x16x32_bf16 v[116:119], v[138:141], v[168:171], v[116:119]
	v_mfma_f32_16x16x32_bf16 v[112:115], v[146:149], v[168:171], v[112:115]
	v_mfma_f32_16x16x32_bf16 v[108:111], v[138:141], v[176:179], v[108:111]
	v_mfma_f32_16x16x32_bf16 v[104:107], v[146:149], v[176:179], v[104:107]
	v_mfma_f32_16x16x32_bf16 v[92:95], v[138:141], v[194:197], v[92:95]
	v_mfma_f32_16x16x32_bf16 v[88:91], v[146:149], v[194:197], v[88:91]
	v_mfma_f32_16x16x32_bf16 v[76:79], v[138:141], v[202:205], v[76:79]
	v_mfma_f32_16x16x32_bf16 v[72:75], v[146:149], v[202:205], v[72:75]
	s_setprio 0
	s_barrier
	s_mov_b32 m0, s54
	v_lshl_add_u64 v[150:151], v[150:151], 0, s[10:11]
	ds_read_b128 v[206:209], v133
	ds_read_b128 v[210:213], v133 offset:1024
	ds_read_b128 v[214:217], v133 offset:2048
	ds_read_b128 v[222:225], v133 offset:3072
	global_load_lds_dwordx4 v[150:151], off
	v_lshl_add_u64 v[150:151], v[180:181], 0, s[10:11]
	s_mov_b32 m0, s55
	s_nop 0
	global_load_lds_dwordx4 v[150:151], off
	s_barrier
	s_waitcnt lgkmcnt(0)
	s_setprio 1
	s_waitcnt lgkmcnt(0)
	v_mfma_f32_16x16x32_bf16 v[124:127], v[206:209], v[164:167], v[124:127]
	v_mfma_f32_16x16x32_bf16 v[120:123], v[214:217], v[164:167], v[120:123]
	v_mfma_f32_16x16x32_bf16 v[100:103], v[206:209], v[172:175], v[100:103]
	v_mfma_f32_16x16x32_bf16 v[96:99], v[214:217], v[172:175], v[96:99]
	v_mfma_f32_16x16x32_bf16 v[84:87], v[206:209], v[190:193], v[84:87]
	v_mfma_f32_16x16x32_bf16 v[80:83], v[214:217], v[190:193], v[80:83]
	v_mfma_f32_16x16x32_bf16 v[68:71], v[206:209], v[198:201], v[68:71]
	v_mfma_f32_16x16x32_bf16 v[64:67], v[214:217], v[198:201], v[64:67]
	v_mfma_f32_16x16x32_bf16 v[124:127], v[210:213], v[168:171], v[124:127]
	v_mfma_f32_16x16x32_bf16 v[120:123], v[222:225], v[168:171], v[120:123]
	v_mfma_f32_16x16x32_bf16 v[100:103], v[210:213], v[176:179], v[100:103]
	v_mfma_f32_16x16x32_bf16 v[96:99], v[222:225], v[176:179], v[96:99]
	v_mfma_f32_16x16x32_bf16 v[84:87], v[210:213], v[194:197], v[84:87]
	v_mfma_f32_16x16x32_bf16 v[80:83], v[222:225], v[194:197], v[80:83]
	v_mfma_f32_16x16x32_bf16 v[68:71], v[210:213], v[202:205], v[68:71]
	v_mfma_f32_16x16x32_bf16 v[64:67], v[222:225], v[202:205], v[64:67]
	s_setprio 0
	s_mov_b32 m0, s42
	v_lshl_add_u64 v[150:151], v[218:219], 0, s[10:11]
	s_barrier
	ds_read_b128 v[164:167], v186 offset:49152
	ds_read_b128 v[168:171], v186 offset:50176
	ds_read_b128 v[172:175], v186 offset:51200
	ds_read_b128 v[176:179], v186 offset:52224
	ds_read_b128 v[190:193], v186 offset:53248
	ds_read_b128 v[194:197], v186 offset:54272
	ds_read_b128 v[198:201], v186 offset:55296
	ds_read_b128 v[202:205], v186 offset:56320
	global_load_lds_dwordx4 v[150:151], off
	v_lshl_add_u64 v[150:151], v[226:227], 0, s[10:11]
	s_mov_b32 m0, s43
	s_nop 0
	global_load_lds_dwordx4 v[150:151], off
	s_barrier
;     ...
;         G_PAIR(0, 1);
; #pragma unroll 1
;         for (int t = 2; t < nt; t += 2) G_PAIR(t, 0);
	s_waitcnt lgkmcnt(0)
	s_setprio 1
	s_waitcnt lgkmcnt(0)
	v_mfma_f32_16x16x32_bf16 v[52:55], v[134:137], v[164:167], v[52:55]
	v_mfma_f32_16x16x32_bf16 v[48:51], v[142:145], v[164:167], v[48:51]
	v_mfma_f32_16x16x32_bf16 v[44:47], v[134:137], v[172:175], v[44:47]
	v_mfma_f32_16x16x32_bf16 v[36:39], v[142:145], v[172:175], v[36:39]
	v_mfma_f32_16x16x32_bf16 v[28:31], v[134:137], v[190:193], v[28:31]
	v_mfma_f32_16x16x32_bf16 v[20:23], v[142:145], v[190:193], v[20:23]
	v_mfma_f32_16x16x32_bf16 v[12:15], v[134:137], v[198:201], v[12:15]
	v_mfma_f32_16x16x32_bf16 v[4:7], v[142:145], v[198:201], v[4:7]
	v_mfma_f32_16x16x32_bf16 v[52:55], v[138:141], v[168:171], v[52:55]
	v_mfma_f32_16x16x32_bf16 v[48:51], v[146:149], v[168:171], v[48:51]
	v_mfma_f32_16x16x32_bf16 v[44:47], v[138:141], v[176:179], v[44:47]
	v_mfma_f32_16x16x32_bf16 v[36:39], v[146:149], v[176:179], v[36:39]
	v_mfma_f32_16x16x32_bf16 v[28:31], v[138:141], v[194:197], v[28:31]
	v_mfma_f32_16x16x32_bf16 v[20:23], v[146:149], v[194:197], v[20:23]
	v_mfma_f32_16x16x32_bf16 v[12:15], v[138:141], v[202:205], v[12:15]
	v_mfma_f32_16x16x32_bf16 v[4:7], v[146:149], v[202:205], v[4:7]
	s_setprio 0
	s_barrier
	s_add_u32 s26, s26, 0xb0080
	s_addc_u32 s27, s27, 0
	s_mov_b32 m0, s56
	v_lshl_add_u64 v[134:135], s[26:27], 0, v[154:155]
	global_load_lds_dwordx4 v[134:135], off
	v_lshl_add_u64 v[134:135], s[26:27], 0, v[158:159]
	s_mov_b32 m0, s57
	s_nop 0
	global_load_lds_dwordx4 v[134:135], off
	s_waitcnt vmcnt(6)
	s_barrier
	s_setprio 1
	v_mfma_f32_16x16x32_bf16 v[60:63], v[206:209], v[164:167], v[60:63]
	v_mfma_f32_16x16x32_bf16 v[56:59], v[214:217], v[164:167], v[56:59]
	v_mfma_f32_16x16x32_bf16 v[40:43], v[206:209], v[172:175], v[40:43]
	v_mfma_f32_16x16x32_bf16 v[32:35], v[214:217], v[172:175], v[32:35]
	v_mfma_f32_16x16x32_bf16 v[24:27], v[206:209], v[190:193], v[24:27]
	v_mfma_f32_16x16x32_bf16 v[16:19], v[214:217], v[190:193], v[16:19]
	v_mfma_f32_16x16x32_bf16 v[8:11], v[206:209], v[198:201], v[8:11]
	v_mfma_f32_16x16x32_bf16 v[0:3], v[214:217], v[198:201], v[0:3]
	v_mfma_f32_16x16x32_bf16 v[60:63], v[210:213], v[168:171], v[60:63]
	v_mfma_f32_16x16x32_bf16 v[56:59], v[222:225], v[168:171], v[56:59]
	v_mfma_f32_16x16x32_bf16 v[40:43], v[210:213], v[176:179], v[40:43]
	v_mfma_f32_16x16x32_bf16 v[32:35], v[222:225], v[176:179], v[32:35]
	v_mfma_f32_16x16x32_bf16 v[24:27], v[210:213], v[194:197], v[24:27]
	v_mfma_f32_16x16x32_bf16 v[16:19], v[222:225], v[194:197], v[16:19]
	v_mfma_f32_16x16x32_bf16 v[8:11], v[210:213], v[202:205], v[8:11]
	v_mfma_f32_16x16x32_bf16 v[0:3], v[222:225], v[202:205], v[0:3]
	s_setprio 0
	s_add_i32 s58, s58, 2
	s_add_u32 s24, s24, 0x100
	s_addc_u32 s25, s25, 0
	s_cmp_gt_u32 s58, 41
	s_barrier
	s_cbranch_scc0 .LBB0_1906
; __device__ __forceinline__ unsigned pk2(float lo, float hi) { unsigned r; asm volatile("v_cvt_pk_bf16_f32 %0, %1, %2" : "=v"(r) : "v"(lo), "v"(hi)); return r; }
; __device__ __forceinline__ unsigned pk2(float lo, float hi) { return f2bf(lo) | (f2bf(hi) << 16); }
;     __device__ __forceinline__ void epi(const f32x4 (&acc)[2][2][4][2], const Unit& u, int wr, int wc, int fr, int fq) const {
;     ...
;         for (int ai = 0; ai < 2; ++ai) {
;             u32x4 xo[4][2];
; #pragma unroll
;             for (int m = 0; m < 4; ++m)
; #pragma unroll
;                 for (int bj = 0; bj < 2; ++bj) xo[m][bj] = *(const u32x4*)(xb + (size_t)(row0 + ai * 128 + m * 16) * D + col0 + bj * 128);
; #pragma unroll
;             for (int m = 0; m < 4; ++m) {
;                 const int row = row0 + ai * 128 + m * 16; const size_t off = (size_t)row * D + col0; float ss = 0.f;
; #pragma unroll
;                 for (int bj = 0; bj < 2; ++bj) {
;                     const u32x4 o = xo[m][bj]; const f32x4 a0v = acc[ai][bj][m][0], a1v = acc[ai][bj][m][1];
;                     const float v0 = bf_lo(o.x) + coef * a0v[0], v1 = bf_hi(o.x) + coef * a0v[1], v2 = bf_lo(o.y) + coef * a0v[2], v3 = bf_hi(o.y) + coef * a0v[3];
;                     const float v4 = bf_lo(o.z) + coef * a1v[0], v5 = bf_hi(o.z) + coef * a1v[1], v6 = bf_lo(o.w) + coef * a1v[2], v7 = bf_hi(o.w) + coef * a1v[3];
;                     u32x4 w; w.x = pk2(v0, v1); w.y = pk2(v2, v3); w.z = pk2(v4, v5); w.w = pk2(v6, v7);
;                     *(u32x4*)(xb + off + bj * 128) = w;
;                     ss += ((v0 * v0 + v1 * v1) + (v2 * v2 + v3 * v3)) + ((v4 * v4 + v5 * v5) + (v6 * v6 + v7 * v7));
;                 }
;                 ss += __shfl_xor(ss, 16); ss += __shfl_xor(ss, 32);
;                 if (fq == 0) rowss[(size_t)row * 32 + u.pn * 4 + wc] = ss;
;             }
	v_lshl_or_b32 v164, s30, 8, v184
	v_lshl_add_u32 v168, s2, 8, v182
	v_ashrrev_i32_e32 v165, 31, v164
	v_lshlrev_b64 v[198:199], 1, v[164:165]
	v_ashrrev_i32_e32 v169, 31, v168
	v_lshl_add_u64 v[166:167], s[0:1], 0, v[198:199]
	v_lshlrev_b64 v[200:201], 11, v[168:169]
	v_lshl_add_u64 v[128:129], v[166:167], 0, v[200:201]
	global_load_dwordx4 v[190:193], v[128:129], off
	global_load_dwordx4 v[194:197], v[128:129], off offset:256
	v_or_b32_e32 v178, 16, v168
	v_or_b32_e32 v174, 32, v168
	v_or_b32_e32 v170, 48, v168
	v_ashrrev_i32_e32 v179, 31, v178
	v_ashrrev_i32_e32 v175, 31, v174
	v_ashrrev_i32_e32 v171, 31, v170
	v_lshlrev_b64 v[180:181], 11, v[178:179]
	v_lshlrev_b64 v[176:177], 11, v[174:175]
	v_lshlrev_b64 v[172:173], 11, v[170:171]
	v_lshl_add_u64 v[128:129], v[166:167], 0, v[180:181]
	v_lshl_add_u64 v[130:131], v[166:167], 0, v[176:177]
	v_lshl_add_u64 v[202:203], v[166:167], 0, v[172:173]
	global_load_dwordx4 v[148:151], v[128:129], off
	global_load_dwordx4 v[144:147], v[128:129], off offset:256
	global_load_dwordx4 v[140:143], v[130:131], off
	global_load_dwordx4 v[136:139], v[130:131], off offset:256
	global_load_dwordx4 v[132:135], v[202:203], off
	s_nop 0
	global_load_dwordx4 v[128:131], v[202:203], off offset:256
	v_and_b32_e32 v202, 64, v188
	v_xor_b32_e32 v189, 16, v188
	v_add_u32_e32 v202, 64, v202
	v_cmp_lt_i32_e32 vcc, v189, v202
	s_waitcnt vmcnt(0)
	v_lshlrev_b32_e32 v203, 16, v190
	v_and_b32_e32 v190, 0xffff0000, v190
	v_lshlrev_b32_e32 v204, 16, v191
	v_and_b32_e32 v191, 0xffff0000, v191
	v_lshlrev_b32_e32 v205, 16, v192
	v_and_b32_e32 v192, 0xffff0000, v192
	v_lshlrev_b32_e32 v206, 16, v193
	v_and_b32_e32 v193, 0xffff0000, v193
	v_lshlrev_b32_e32 v207, 16, v194
	v_and_b32_e32 v194, 0xffff0000, v194
	v_lshlrev_b32_e32 v208, 16, v195
	v_and_b32_e32 v195, 0xffff0000, v195
	v_lshlrev_b32_e32 v209, 16, v196
	v_and_b32_e32 v196, 0xffff0000, v196
	v_lshlrev_b32_e32 v210, 16, v197
	v_and_b32_e32 v197, 0xffff0000, v197
	v_fmac_f32_e32 v190, 0.5, v117
	v_fmac_f32_e32 v191, 0.5, v119
	v_fmac_f32_e32 v192, 0.5, v113
	v_fmac_f32_e32 v193, 0.5, v115
	v_fmac_f32_e32 v194, 0.5, v125
	v_fmac_f32_e32 v195, 0.5, v127
	v_fmac_f32_e32 v196, 0.5, v121
	v_fmac_f32_e32 v197, 0.5, v123
	v_fmac_f32_e32 v203, 0.5, v116
	v_fmac_f32_e32 v204, 0.5, v118
	v_fmac_f32_e32 v205, 0.5, v112
	v_fmac_f32_e32 v206, 0.5, v114
	v_fmac_f32_e32 v207, 0.5, v124
	v_fmac_f32_e32 v208, 0.5, v126
	v_fmac_f32_e32 v209, 0.5, v120
	v_fmac_f32_e32 v210, 0.5, v122
	v_mul_f32_e32 v112, v190, v190
	v_mul_f32_e32 v113, v191, v191
	v_mul_f32_e32 v118, v192, v192
	v_mul_f32_e32 v119, v193, v193
	v_mul_f32_e32 v120, v194, v194
	v_mul_f32_e32 v121, v195, v195
	v_mul_f32_e32 v122, v196, v196
	v_mul_f32_e32 v123, v197, v197
	v_fmac_f32_e32 v112, v203, v203
	v_fmac_f32_e32 v113, v204, v204
	v_fmac_f32_e32 v118, v205, v205
	v_fmac_f32_e32 v119, v206, v206
	v_fmac_f32_e32 v120, v207, v207
	v_fmac_f32_e32 v121, v208, v208
	v_fmac_f32_e32 v122, v209, v209
	v_fmac_f32_e32 v123, v210, v210
	v_add_f32_e32 v112, v112, v113
	v_add_f32_e32 v113, v118, v119
	v_add_f32_e32 v118, v120, v121
	v_add_f32_e32 v119, v122, v123
	v_cndmask_b32_e32 v189, v188, v189, vcc
	v_add_f32_e32 v112, v112, v113
	v_add_f32_e32 v113, v118, v119
	v_add_f32_e32 v113, v112, v113
	v_lshlrev_b32_e32 v112, 2, v189
	ds_bpermute_b32 v122, v112, v113
	v_lshl_add_u64 v[118:119], s[0:1], 0, v[200:201]
	v_cvt_pk_bf16_f32 v114, v203, v190
	v_lshl_add_u64 v[120:121], v[118:119], 0, v[198:199]
	v_cvt_pk_bf16_f32 v115, v204, v191
	v_cvt_pk_bf16_f32 v116, v205, v192
	v_cvt_pk_bf16_f32 v117, v206, v193
	global_store_dwordx4 v[120:121], v[114:117], off
	s_waitcnt lgkmcnt(0)
	s_nop 0
	v_add_f32_e32 v114, v113, v122
	v_xor_b32_e32 v113, 32, v188
	v_cmp_lt_i32_e32 vcc, v113, v202
	v_cvt_pk_bf16_f32 v116, v207, v194
	v_cvt_pk_bf16_f32 v117, v208, v195
	v_cvt_pk_bf16_f32 v118, v209, v196
	v_cvt_pk_bf16_f32 v119, v210, v197
	global_store_dwordx4 v[120:121], v[116:119], off offset:256
	s_nop 0
	v_cndmask_b32_e32 v113, v188, v113, vcc
	v_lshlrev_b32_e32 v113, 2, v113
	ds_bpermute_b32 v115, v113, v114
	s_and_saveexec_b64 s[20:21], s[4:5]
	s_cbranch_execz .LBB0_1909
	s_waitcnt lgkmcnt(0)
	v_add_f32_e32 v116, v114, v115
	s_lshl_b32 s22, s30, 2
	v_lshlrev_b64 v[114:115], 7, v[168:169]
	s_ashr_i32 s23, s22, 31
	v_lshl_add_u64 v[114:115], s[8:9], 0, v[114:115]
	v_lshl_add_u64 v[114:115], s[22:23], 2, v[114:115]
	s_lshl_b32 s2, s41, 2
	v_lshl_add_u64 v[114:115], v[114:115], 0, s[2:3]
	global_store_dword v[114:115], v116, off
